# loop-edge rotation in the 8 SS_LDS GEMM K-loops: pointer advances and last-iteration flag computed at the end of the last load section (before the barrier) instead of after the loop-back barrier
# baseline (speedup 1.0000x reference)
; #define LAS __attribute__((address_space(3)))
; #define PG8_STAGE(bufoff, gbase, voff) do { _Pragma("unroll") for (int _i = 0; _i < 2; ++_i) \
;         __builtin_amdgcn_global_load_lds((const unsigned*)((const char*)(gbase) + (voff)[_i]), (LAS unsigned*)(lds + (bufoff) + ldsw + _i * 8192), 16, 0, 0); } while (0)
; #define PG8_LDA(dst, b, h) do { _Pragma("unroll") for (int m = 0; m < 4; ++m) _Pragma("unroll") for (int k = 0; k < 2; ++k) dst[m][k] = *(const LAS bf16x8*)(lds + PG8_SA(b, h) + aoff + m * 2048 + k * 1024); } while (0)
; #define PG8_LDB(dst, b, h) do { _Pragma("unroll") for (int n = 0; n < 2; ++n) _Pragma("unroll") for (int k = 0; k < 2; ++k) dst[n][k] = *(const LAS bf16x8*)(lds + PG8_SB(b, h) + boff + n * 2048 + k * 1024); } while (0)
; #define PG8_WAIT_V(n) asm volatile("s_waitcnt vmcnt(" #n ")" ::: "memory")
; #define PG8_WAIT_L(n) asm volatile("s_waitcnt lgkmcnt(" #n ")" ::: "memory")
; template <class Epi>
; __device__ __forceinline__ void gemm_phase(LAS unsigned char* lds, const int tid, const Gemm g, const StaticOrder& S, const Epi& E) {
;     ...
;         for (int t = 0; t < nt; t += 2) {
;             const bool last = (t == nt - 2);
;             const char* a1 = cA + (size_t)(t + 1) * kstep;
;             const char* a2 = last ? nA : cA + (size_t)(t + 2) * kstep; const char* b2 = last ? nB : cB + (size_t)(t + 2) * kstep;
;             const char* a3 = a2 + kstep; const char* b3 = b2 + kstep;
;             if constexpr (Epi::SS_LDS) { if (last) {
;                 const char* sp = (const char*)E.ss + (size_t)cur.pm * (256 * 64) + (size_t)tid * 16;
;                 __builtin_amdgcn_global_load_lds((const unsigned*)sp, (LAS unsigned*)(lds + RS_OFF + ldsw), 16, 0, 0);
;                 __builtin_amdgcn_global_load_lds((const unsigned*)(sp + 8192), (LAS unsigned*)(lds + RS_OFF + 8192 + ldsw), 16, 0, 0); } }
;     ...
;             PG8_LDB(B0, 0, 0); PG8_LDB(B1, 0, 1); PG8_SCHED; PG8_LDA(At, 0, 0); PG8_STAGE(PG8_SA(1, 1), a1 + hstepA, voffA);
;             PG8_WAIT_V(8); PG8_WAIT_L(0); PG8_BAR; PG8_MMA(0, 0, At, B0); PG8_MMA(0, 1, At, B1); PG8_BAR; PG8_SCHED;
;             PG8_LDA(At, 0, 1); PG8_STAGE(PG8_SB(0, 0), b2, voffB); PG8_STAGE(PG8_SB(0, 1), b2 + hstepB, voffB); PG8_STAGE(PG8_SA(0, 0), a2, voffA);
;             PG8_WAIT_V(8); PG8_WAIT_L(0); PG8_BAR; PG8_MMA(1, 0, At, B0); PG8_MMA(1, 1, At, B1); PG8_BAR; PG8_SCHED;
.LBB0_263:
	v_add_u32_e32 v168, s51, v151
	v_add_u32_e32 v184, s52, v151
	ds_read_b128 v[156:159], v168
	ds_read_b128 v[160:163], v168 offset:1024
	ds_read_b128 v[164:167], v168 offset:2048
	ds_read_b128 v[168:171], v168 offset:3072
	ds_read_b128 v[172:175], v184
	ds_read_b128 v[176:179], v184 offset:1024
	ds_read_b128 v[180:183], v184 offset:2048
	ds_read_b128 v[184:187], v184 offset:3072
	s_add_i32 s58, s58, 2
	s_add_u32 s30, s26, 0xfffc0080
	s_addc_u32 s31, s27, -1
	s_and_b64 s[28:29], s[28:29], exec
	s_cselect_b32 s31, s17, s31
	s_cselect_b32 s30, s19, s30
	s_cselect_b32 s29, s55, s57
	s_cselect_b32 s28, s56, s25
	v_lshl_add_u64 v[220:221], s[26:27], 0, v[140:141]
	s_add_i32 m0, s41, 0xc000
	ds_read_b128 v[188:191], v153
	ds_read_b128 v[192:195], v153 offset:1024
	ds_read_b128 v[196:199], v153 offset:2048
	ds_read_b128 v[200:203], v153 offset:3072
	ds_read_b128 v[204:207], v153 offset:4096
	ds_read_b128 v[208:211], v153 offset:5120
	ds_read_b128 v[212:215], v153 offset:6144
	ds_read_b128 v[216:219], v153 offset:7168
	global_load_lds_dwordx4 v[220:221], off
	v_lshl_add_u64 v[220:221], s[26:27], 0, v[138:139]
	s_add_i32 m0, s41, 0xe000
	s_nop 0
	global_load_lds_dwordx4 v[220:221], off
	s_waitcnt vmcnt(8)
	s_waitcnt lgkmcnt(0)
	s_barrier
	s_setprio 1
	v_mfma_f32_16x16x32_bf16 v[120:123], v[156:159], v[188:191], v[120:123]
	v_mfma_f32_16x16x32_bf16 v[116:119], v[164:167], v[188:191], v[116:119]
	v_mfma_f32_16x16x32_bf16 v[108:111], v[156:159], v[196:199], v[108:111]
	v_mfma_f32_16x16x32_bf16 v[100:103], v[164:167], v[196:199], v[100:103]
	v_mfma_f32_16x16x32_bf16 v[92:95], v[156:159], v[204:207], v[92:95]
	v_mfma_f32_16x16x32_bf16 v[84:87], v[164:167], v[204:207], v[84:87]
	v_mfma_f32_16x16x32_bf16 v[76:79], v[156:159], v[212:215], v[76:79]
	v_mfma_f32_16x16x32_bf16 v[68:71], v[164:167], v[212:215], v[68:71]
	v_mfma_f32_16x16x32_bf16 v[120:123], v[160:163], v[192:195], v[120:123]
	v_mfma_f32_16x16x32_bf16 v[116:119], v[168:171], v[192:195], v[116:119]
	v_mfma_f32_16x16x32_bf16 v[108:111], v[160:163], v[200:203], v[108:111]
	v_mfma_f32_16x16x32_bf16 v[100:103], v[168:171], v[200:203], v[100:103]
	v_mfma_f32_16x16x32_bf16 v[92:95], v[160:163], v[208:211], v[92:95]
	v_mfma_f32_16x16x32_bf16 v[84:87], v[168:171], v[208:211], v[84:87]
	v_mfma_f32_16x16x32_bf16 v[76:79], v[160:163], v[216:219], v[76:79]
	v_mfma_f32_16x16x32_bf16 v[68:71], v[168:171], v[216:219], v[68:71]
	v_mfma_f32_16x16x32_bf16 v[124:127], v[172:175], v[188:191], v[124:127]
	v_mfma_f32_16x16x32_bf16 v[112:115], v[180:183], v[188:191], v[112:115]
	v_mfma_f32_16x16x32_bf16 v[104:107], v[172:175], v[196:199], v[104:107]
	v_mfma_f32_16x16x32_bf16 v[96:99], v[180:183], v[196:199], v[96:99]
	v_mfma_f32_16x16x32_bf16 v[88:91], v[172:175], v[204:207], v[88:91]
	v_mfma_f32_16x16x32_bf16 v[80:83], v[180:183], v[204:207], v[80:83]
	v_mfma_f32_16x16x32_bf16 v[72:75], v[172:175], v[212:215], v[72:75]
	v_mfma_f32_16x16x32_bf16 v[64:67], v[180:183], v[212:215], v[64:67]
	v_mfma_f32_16x16x32_bf16 v[124:127], v[176:179], v[192:195], v[124:127]
	v_mfma_f32_16x16x32_bf16 v[112:115], v[184:187], v[192:195], v[112:115]
	v_mfma_f32_16x16x32_bf16 v[104:107], v[176:179], v[200:203], v[104:107]
	v_mfma_f32_16x16x32_bf16 v[96:99], v[184:187], v[200:203], v[96:99]
	v_mfma_f32_16x16x32_bf16 v[88:91], v[176:179], v[208:211], v[88:91]
	v_mfma_f32_16x16x32_bf16 v[80:83], v[184:187], v[208:211], v[80:83]
	v_mfma_f32_16x16x32_bf16 v[72:75], v[176:179], v[216:219], v[72:75]
	v_mfma_f32_16x16x32_bf16 v[64:67], v[184:187], v[216:219], v[64:67]
	s_setprio 0
	s_barrier
	s_add_i32 s59, s51, s38
	v_lshl_add_u64 v[220:221], s[28:29], 0, v[132:133]
	s_mov_b32 m0, s59
	ds_read_b128 v[188:191], v153 offset:16384
	ds_read_b128 v[192:195], v153 offset:17408
	ds_read_b128 v[196:199], v153 offset:18432
	ds_read_b128 v[200:203], v153 offset:19456
	ds_read_b128 v[204:207], v153 offset:20480
	ds_read_b128 v[208:211], v153 offset:21504
	ds_read_b128 v[212:215], v153 offset:22528
	ds_read_b128 v[216:219], v153 offset:23552
	global_load_lds_dwordx4 v[220:221], off
	s_add_i32 m0, s59, 0x2000
	s_add_u32 s60, s28, 0x40000
	v_lshl_add_u64 v[222:223], s[28:29], 0, v[128:129]
	s_addc_u32 s61, s29, 0
	s_add_i32 s59, s52, s38
	global_load_lds_dwordx4 v[222:223], off
	v_lshl_add_u64 v[224:225], s[60:61], 0, v[132:133]
	s_mov_b32 m0, s59
	v_lshl_add_u64 v[226:227], s[30:31], 0, v[130:131]
	global_load_lds_dwordx4 v[224:225], off
	v_lshl_add_u64 v[224:225], s[60:61], 0, v[128:129]
	s_add_i32 m0, s59, 0x2000
	s_nop 0
	global_load_lds_dwordx4 v[224:225], off
	v_lshl_add_u64 v[224:225], s[30:31], 0, v[134:135]
	s_mov_b32 m0, s41
	s_nop 0
	global_load_lds_dwordx4 v[224:225], off
	s_mov_b32 m0, s42
	s_nop 0
	global_load_lds_dwordx4 v[226:227], off
	s_waitcnt vmcnt(8)
	s_waitcnt lgkmcnt(0)
	s_barrier
; #define PG8_STAGE(bufoff, gbase, voff) do { _Pragma("unroll") for (int _i = 0; _i < 2; ++_i) \
;         __builtin_amdgcn_global_load_lds((const unsigned*)((const char*)(gbase) + (voff)[_i]), (LAS unsigned*)(lds + (bufoff) + ldsw + _i * 8192), 16, 0, 0); } while (0)
; #define PG8_LDA(dst, b, h) do { _Pragma("unroll") for (int m = 0; m < 4; ++m) _Pragma("unroll") for (int k = 0; k < 2; ++k) dst[m][k] = *(const LAS bf16x8*)(lds + PG8_SA(b, h) + aoff + m * 2048 + k * 1024); } while (0)
; #define PG8_LDB(dst, b, h) do { _Pragma("unroll") for (int n = 0; n < 2; ++n) _Pragma("unroll") for (int k = 0; k < 2; ++k) dst[n][k] = *(const LAS bf16x8*)(lds + PG8_SB(b, h) + boff + n * 2048 + k * 1024); } while (0)
; #define PG8_MMA(ai, bj, At, Bt) do { __builtin_amdgcn_s_setprio(1); _Pragma("unroll") for (int m = 0; m < 4; ++m) _Pragma("unroll") for (int n = 0; n < 2; ++n) _Pragma("unroll") for (int k = 0; k < 2; ++k) \
;         acc[ai][bj][m][n] = __builtin_amdgcn_mfma_f32_16x16x32_bf16(Bt[n][k], At[m][k], acc[ai][bj][m][n], 0, 0, 0); __builtin_amdgcn_s_setprio(0); } while (0)
; #define PG8_WAIT_V(n) asm volatile("s_waitcnt vmcnt(" #n ")" ::: "memory")
; #define PG8_WAIT_L(n) asm volatile("s_waitcnt lgkmcnt(" #n ")" ::: "memory")
; #define PG8_BAR __builtin_amdgcn_s_barrier()
; #define PG8_SCHED __builtin_amdgcn_sched_barrier(0)
; template <class Epi>
; __device__ __forceinline__ void gemm_phase(LAS unsigned char* lds, const int tid, const Gemm g, const StaticOrder& S, const Epi& E) {
;     ...
;             PG8_WAIT_V(8); PG8_WAIT_L(0); PG8_BAR; PG8_MMA(1, 0, At, B0); PG8_MMA(1, 1, At, B1); PG8_BAR; PG8_SCHED;
;             PG8_LDB(B0, 1, 0); PG8_LDB(B1, 1, 1); PG8_SCHED; PG8_LDA(At, 1, 0); PG8_STAGE(PG8_SA(0, 1), a2 + hstepA, voffA);
;             PG8_WAIT_V(8); PG8_WAIT_L(0); PG8_BAR; PG8_MMA(0, 0, At, B0); PG8_MMA(0, 1, At, B1); PG8_BAR; PG8_SCHED;
	s_setprio 1
	v_mfma_f32_16x16x32_bf16 v[60:63], v[156:159], v[188:191], v[60:63]
	v_mfma_f32_16x16x32_bf16 v[52:55], v[164:167], v[188:191], v[52:55]
	v_mfma_f32_16x16x32_bf16 v[44:47], v[156:159], v[196:199], v[44:47]
	v_mfma_f32_16x16x32_bf16 v[36:39], v[164:167], v[196:199], v[36:39]
	v_mfma_f32_16x16x32_bf16 v[28:31], v[156:159], v[204:207], v[28:31]
	v_mfma_f32_16x16x32_bf16 v[20:23], v[164:167], v[204:207], v[20:23]
	v_mfma_f32_16x16x32_bf16 v[12:15], v[156:159], v[212:215], v[12:15]
	v_mfma_f32_16x16x32_bf16 v[4:7], v[164:167], v[212:215], v[4:7]
	v_mfma_f32_16x16x32_bf16 v[60:63], v[160:163], v[192:195], v[60:63]
	v_mfma_f32_16x16x32_bf16 v[52:55], v[168:171], v[192:195], v[52:55]
	v_mfma_f32_16x16x32_bf16 v[44:47], v[160:163], v[200:203], v[44:47]
	v_mfma_f32_16x16x32_bf16 v[36:39], v[168:171], v[200:203], v[36:39]
	v_mfma_f32_16x16x32_bf16 v[28:31], v[160:163], v[208:211], v[28:31]
	v_mfma_f32_16x16x32_bf16 v[20:23], v[168:171], v[208:211], v[20:23]
	v_mfma_f32_16x16x32_bf16 v[12:15], v[160:163], v[216:219], v[12:15]
	v_mfma_f32_16x16x32_bf16 v[4:7], v[168:171], v[216:219], v[4:7]
	v_mfma_f32_16x16x32_bf16 v[56:59], v[172:175], v[188:191], v[56:59]
	v_mfma_f32_16x16x32_bf16 v[48:51], v[180:183], v[188:191], v[48:51]
	v_mfma_f32_16x16x32_bf16 v[40:43], v[172:175], v[196:199], v[40:43]
	v_mfma_f32_16x16x32_bf16 v[32:35], v[180:183], v[196:199], v[32:35]
	v_mfma_f32_16x16x32_bf16 v[24:27], v[172:175], v[204:207], v[24:27]
	v_mfma_f32_16x16x32_bf16 v[16:19], v[180:183], v[204:207], v[16:19]
	v_mfma_f32_16x16x32_bf16 v[8:11], v[172:175], v[212:215], v[8:11]
	v_mfma_f32_16x16x32_bf16 v[0:3], v[180:183], v[212:215], v[0:3]
	v_mfma_f32_16x16x32_bf16 v[56:59], v[176:179], v[192:195], v[56:59]
	v_mfma_f32_16x16x32_bf16 v[48:51], v[184:187], v[192:195], v[48:51]
	v_mfma_f32_16x16x32_bf16 v[40:43], v[176:179], v[200:203], v[40:43]
	v_mfma_f32_16x16x32_bf16 v[32:35], v[184:187], v[200:203], v[32:35]
	v_mfma_f32_16x16x32_bf16 v[24:27], v[176:179], v[208:211], v[24:27]
	v_mfma_f32_16x16x32_bf16 v[16:19], v[184:187], v[208:211], v[16:19]
	v_mfma_f32_16x16x32_bf16 v[8:11], v[176:179], v[216:219], v[8:11]
	v_mfma_f32_16x16x32_bf16 v[0:3], v[184:187], v[216:219], v[0:3]
	s_setprio 0
	s_barrier
	s_add_i32 s59, 0, 0x18000
	s_add_i32 s60, 0, 0x1c000
	v_add_u32_e32 v168, s59, v151
	v_add_u32_e32 v184, s60, v151
	ds_read_b128 v[156:159], v168
	ds_read_b128 v[160:163], v168 offset:1024
	ds_read_b128 v[164:167], v168 offset:2048
	ds_read_b128 v[168:171], v168 offset:3072
	ds_read_b128 v[172:175], v184
	ds_read_b128 v[176:179], v184 offset:1024
	ds_read_b128 v[180:183], v184 offset:2048
	ds_read_b128 v[184:187], v184 offset:3072
	s_add_u32 s30, s30, 0x40000
	s_addc_u32 s31, s31, 0
	s_mov_b32 m0, s43
	v_lshl_add_u64 v[228:229], s[30:31], 0, v[134:135]
	ds_read_b128 v[188:191], v153 offset:32768
	ds_read_b128 v[192:195], v153 offset:33792
	ds_read_b128 v[196:199], v153 offset:34816
	ds_read_b128 v[200:203], v153 offset:35840
	ds_read_b128 v[204:207], v153 offset:36864
	ds_read_b128 v[208:211], v153 offset:37888
	ds_read_b128 v[212:215], v153 offset:38912
	ds_read_b128 v[216:219], v153 offset:39936
	global_load_lds_dwordx4 v[228:229], off
	v_lshl_add_u64 v[228:229], s[30:31], 0, v[130:131]
	s_mov_b32 m0, s44
	s_nop 0
	global_load_lds_dwordx4 v[228:229], off
	s_waitcnt vmcnt(8)
	s_waitcnt lgkmcnt(0)
	s_barrier
	s_setprio 1
	v_mfma_f32_16x16x32_bf16 v[120:123], v[156:159], v[188:191], v[120:123]
	v_mfma_f32_16x16x32_bf16 v[116:119], v[164:167], v[188:191], v[116:119]
	v_mfma_f32_16x16x32_bf16 v[108:111], v[156:159], v[196:199], v[108:111]
	v_mfma_f32_16x16x32_bf16 v[100:103], v[164:167], v[196:199], v[100:103]
	v_mfma_f32_16x16x32_bf16 v[92:95], v[156:159], v[204:207], v[92:95]
	v_mfma_f32_16x16x32_bf16 v[84:87], v[164:167], v[204:207], v[84:87]
	v_mfma_f32_16x16x32_bf16 v[76:79], v[156:159], v[212:215], v[76:79]
	v_mfma_f32_16x16x32_bf16 v[68:71], v[164:167], v[212:215], v[68:71]
	v_mfma_f32_16x16x32_bf16 v[120:123], v[160:163], v[192:195], v[120:123]
	v_mfma_f32_16x16x32_bf16 v[116:119], v[168:171], v[192:195], v[116:119]
	v_mfma_f32_16x16x32_bf16 v[108:111], v[160:163], v[200:203], v[108:111]
	v_mfma_f32_16x16x32_bf16 v[100:103], v[168:171], v[200:203], v[100:103]
	v_mfma_f32_16x16x32_bf16 v[92:95], v[160:163], v[208:211], v[92:95]
	v_mfma_f32_16x16x32_bf16 v[84:87], v[168:171], v[208:211], v[84:87]
	v_mfma_f32_16x16x32_bf16 v[76:79], v[160:163], v[216:219], v[76:79]
	v_mfma_f32_16x16x32_bf16 v[68:71], v[168:171], v[216:219], v[68:71]
	v_mfma_f32_16x16x32_bf16 v[124:127], v[172:175], v[188:191], v[124:127]
	v_mfma_f32_16x16x32_bf16 v[112:115], v[180:183], v[188:191], v[112:115]
	v_mfma_f32_16x16x32_bf16 v[104:107], v[172:175], v[196:199], v[104:107]
	v_mfma_f32_16x16x32_bf16 v[96:99], v[180:183], v[196:199], v[96:99]
	v_mfma_f32_16x16x32_bf16 v[88:91], v[172:175], v[204:207], v[88:91]
	v_mfma_f32_16x16x32_bf16 v[80:83], v[180:183], v[204:207], v[80:83]
	v_mfma_f32_16x16x32_bf16 v[72:75], v[172:175], v[212:215], v[72:75]
	v_mfma_f32_16x16x32_bf16 v[64:67], v[180:183], v[212:215], v[64:67]
	v_mfma_f32_16x16x32_bf16 v[124:127], v[176:179], v[192:195], v[124:127]
	v_mfma_f32_16x16x32_bf16 v[112:115], v[184:187], v[192:195], v[112:115]
	v_mfma_f32_16x16x32_bf16 v[104:107], v[176:179], v[200:203], v[104:107]
	v_mfma_f32_16x16x32_bf16 v[96:99], v[184:187], v[200:203], v[96:99]
	v_mfma_f32_16x16x32_bf16 v[88:91], v[176:179], v[208:211], v[88:91]
	v_mfma_f32_16x16x32_bf16 v[80:83], v[184:187], v[208:211], v[80:83]
	v_mfma_f32_16x16x32_bf16 v[72:75], v[176:179], v[216:219], v[72:75]
	v_mfma_f32_16x16x32_bf16 v[64:67], v[184:187], v[216:219], v[64:67]
	s_setprio 0
	s_barrier
; #define PG8_STAGE(bufoff, gbase, voff) do { _Pragma("unroll") for (int _i = 0; _i < 2; ++_i) \
;         __builtin_amdgcn_global_load_lds((const unsigned*)((const char*)(gbase) + (voff)[_i]), (LAS unsigned*)(lds + (bufoff) + ldsw + _i * 8192), 16, 0, 0); } while (0)
; #define PG8_LDA(dst, b, h) do { _Pragma("unroll") for (int m = 0; m < 4; ++m) _Pragma("unroll") for (int k = 0; k < 2; ++k) dst[m][k] = *(const LAS bf16x8*)(lds + PG8_SA(b, h) + aoff + m * 2048 + k * 1024); } while (0)
; #define PG8_MMA(ai, bj, At, Bt) do { __builtin_amdgcn_s_setprio(1); _Pragma("unroll") for (int m = 0; m < 4; ++m) _Pragma("unroll") for (int n = 0; n < 2; ++n) _Pragma("unroll") for (int k = 0; k < 2; ++k) \
;         acc[ai][bj][m][n] = __builtin_amdgcn_mfma_f32_16x16x32_bf16(Bt[n][k], At[m][k], acc[ai][bj][m][n], 0, 0, 0); __builtin_amdgcn_s_setprio(0); } while (0)
; #define PG8_WAIT_V(n) asm volatile("s_waitcnt vmcnt(" #n ")" ::: "memory")
; #define PG8_WAIT_L(n) asm volatile("s_waitcnt lgkmcnt(" #n ")" ::: "memory")
; #define PG8_BAR __builtin_amdgcn_s_barrier()
; #define PG8_SCHED __builtin_amdgcn_sched_barrier(0)
; template <class Epi>
; __device__ __forceinline__ void gemm_phase(LAS unsigned char* lds, const int tid, const Gemm g, const StaticOrder& S, const Epi& E) {
;     ...
;         for (int t = 0; t < nt; t += 2) {
;             const bool last = (t == nt - 2);
;             const char* a1 = cA + (size_t)(t + 1) * kstep;
;             const char* a2 = last ? nA : cA + (size_t)(t + 2) * kstep; const char* b2 = last ? nB : cB + (size_t)(t + 2) * kstep;
;     ...
;             PG8_LDA(At, 1, 1); PG8_STAGE(PG8_SB(1, 0), b3, voffB); PG8_STAGE(PG8_SB(1, 1), b3 + hstepB, voffB); PG8_STAGE(PG8_SA(1, 0), a3, voffA);
;             PG8_WAIT_V(8); PG8_WAIT_L(0); PG8_BAR; PG8_MMA(1, 0, At, B0); PG8_MMA(1, 1, At, B1); PG8_BAR; PG8_SCHED;
	s_add_i32 s30, s59, s38
	v_lshl_add_u64 v[220:221], v[220:221], 0, s[12:13]
	s_mov_b32 m0, s30
	ds_read_b128 v[188:191], v153 offset:49152
	ds_read_b128 v[192:195], v153 offset:50176
	ds_read_b128 v[196:199], v153 offset:51200
	ds_read_b128 v[200:203], v153 offset:52224
	ds_read_b128 v[204:207], v153 offset:53248
	ds_read_b128 v[208:211], v153 offset:54272
	ds_read_b128 v[212:215], v153 offset:55296
	ds_read_b128 v[216:219], v153 offset:56320
	global_load_lds_dwordx4 v[220:221], off
	s_add_i32 m0, s30, 0x2000
	s_add_u32 s28, s28, 0x40080
	v_lshl_add_u64 v[220:221], v[222:223], 0, s[12:13]
	s_addc_u32 s29, s29, 0
	s_add_i32 s30, s60, s38
	global_load_lds_dwordx4 v[220:221], off
	v_lshl_add_u64 v[220:221], s[28:29], 0, v[132:133]
	s_mov_b32 m0, s30
	s_nop 0
	global_load_lds_dwordx4 v[220:221], off
	v_lshl_add_u64 v[220:221], s[28:29], 0, v[128:129]
	s_add_i32 m0, s30, 0x2000
	s_nop 0
	global_load_lds_dwordx4 v[220:221], off
	v_lshl_add_u64 v[220:221], v[224:225], 0, s[12:13]
	s_mov_b32 m0, s47
	s_nop 0
	global_load_lds_dwordx4 v[220:221], off
	v_lshl_add_u64 v[220:221], v[226:227], 0, s[12:13]
	s_mov_b32 m0, s48
	s_nop 0
	global_load_lds_dwordx4 v[220:221], off
	s_add_u32 s25, s25, 0x100
	s_addc_u32 s57, s57, 0
	s_add_u32 s26, s26, 0x100
	s_addc_u32 s27, s27, 0
	s_cmp_eq_u32 s49, s58
	s_cselect_b64 s[28:29], -1, 0
	s_waitcnt vmcnt(8)
	s_waitcnt lgkmcnt(0)
	s_barrier
	s_setprio 1
	v_mfma_f32_16x16x32_bf16 v[60:63], v[156:159], v[188:191], v[60:63]
	v_mfma_f32_16x16x32_bf16 v[52:55], v[164:167], v[188:191], v[52:55]
	v_mfma_f32_16x16x32_bf16 v[44:47], v[156:159], v[196:199], v[44:47]
	v_mfma_f32_16x16x32_bf16 v[36:39], v[164:167], v[196:199], v[36:39]
	v_mfma_f32_16x16x32_bf16 v[28:31], v[156:159], v[204:207], v[28:31]
	v_mfma_f32_16x16x32_bf16 v[20:23], v[164:167], v[204:207], v[20:23]
	v_mfma_f32_16x16x32_bf16 v[12:15], v[156:159], v[212:215], v[12:15]
	v_mfma_f32_16x16x32_bf16 v[4:7], v[164:167], v[212:215], v[4:7]
	v_mfma_f32_16x16x32_bf16 v[60:63], v[160:163], v[192:195], v[60:63]
	v_mfma_f32_16x16x32_bf16 v[52:55], v[168:171], v[192:195], v[52:55]
	v_mfma_f32_16x16x32_bf16 v[44:47], v[160:163], v[200:203], v[44:47]
	v_mfma_f32_16x16x32_bf16 v[36:39], v[168:171], v[200:203], v[36:39]
	v_mfma_f32_16x16x32_bf16 v[28:31], v[160:163], v[208:211], v[28:31]
	v_mfma_f32_16x16x32_bf16 v[20:23], v[168:171], v[208:211], v[20:23]
	v_mfma_f32_16x16x32_bf16 v[12:15], v[160:163], v[216:219], v[12:15]
	v_mfma_f32_16x16x32_bf16 v[4:7], v[168:171], v[216:219], v[4:7]
	v_mfma_f32_16x16x32_bf16 v[56:59], v[172:175], v[188:191], v[56:59]
	v_mfma_f32_16x16x32_bf16 v[48:51], v[180:183], v[188:191], v[48:51]
	v_mfma_f32_16x16x32_bf16 v[40:43], v[172:175], v[196:199], v[40:43]
	v_mfma_f32_16x16x32_bf16 v[32:35], v[180:183], v[196:199], v[32:35]
	v_mfma_f32_16x16x32_bf16 v[24:27], v[172:175], v[204:207], v[24:27]
	v_mfma_f32_16x16x32_bf16 v[16:19], v[180:183], v[204:207], v[16:19]
	v_mfma_f32_16x16x32_bf16 v[8:11], v[172:175], v[212:215], v[8:11]
	v_mfma_f32_16x16x32_bf16 v[0:3], v[180:183], v[212:215], v[0:3]
	v_mfma_f32_16x16x32_bf16 v[56:59], v[176:179], v[192:195], v[56:59]
	v_mfma_f32_16x16x32_bf16 v[48:51], v[184:187], v[192:195], v[48:51]
	v_mfma_f32_16x16x32_bf16 v[40:43], v[176:179], v[200:203], v[40:43]
	v_mfma_f32_16x16x32_bf16 v[32:35], v[184:187], v[200:203], v[32:35]
	v_mfma_f32_16x16x32_bf16 v[24:27], v[176:179], v[208:211], v[24:27]
	v_mfma_f32_16x16x32_bf16 v[16:19], v[184:187], v[208:211], v[16:19]
	v_mfma_f32_16x16x32_bf16 v[8:11], v[176:179], v[216:219], v[8:11]
	v_mfma_f32_16x16x32_bf16 v[0:3], v[184:187], v[216:219], v[0:3]
	s_setprio 0
	s_barrier
	s_cmp_ge_i32 s58, s46
	s_cbranch_scc1 .LBB0_266
	s_cmp_lg_u32 s49, s58
	s_cbranch_scc1 .LBB0_263
	s_branch .Lrs_1

; #define LAS __attribute__((address_space(3)))
; template <class Epi>
; __device__ __forceinline__ void gemm_phase(LAS unsigned char* lds, const int tid, const Gemm g, const StaticOrder& S, const Epi& E) {
;     ...
;             if constexpr (Epi::SS_LDS) { if (last) {
;                 const char* sp = (const char*)E.ss + (size_t)cur.pm * (256 * 64) + (size_t)tid * 16;
;                 __builtin_amdgcn_global_load_lds((const unsigned*)sp, (LAS unsigned*)(lds + RS_OFF + ldsw), 16, 0, 0);
;                 __builtin_amdgcn_global_load_lds((const unsigned*)(sp + 8192), (LAS unsigned*)(lds + RS_OFF + 8192 + ldsw), 16, 0, 0); } }
.Lrs_1:
	s_add_i32 m0, s41, 0x20800
	s_nop 0
	global_load_lds_dwordx4 v[146:147], off
	s_add_i32 m0, s41, 0x22800
	s_nop 0
	global_load_lds_dwordx4 v[148:149], off
	s_branch .LBB0_263

; #define LAS __attribute__((address_space(3)))
; #define PG8_STAGE(bufoff, gbase, voff) do { _Pragma("unroll") for (int _i = 0; _i < 2; ++_i) \
;         __builtin_amdgcn_global_load_lds((const unsigned*)((const char*)(gbase) + (voff)[_i]), (LAS unsigned*)(lds + (bufoff) + ldsw + _i * 8192), 16, 0, 0); } while (0)
; #define PG8_LDA(dst, b, h) do { _Pragma("unroll") for (int m = 0; m < 4; ++m) _Pragma("unroll") for (int k = 0; k < 2; ++k) dst[m][k] = *(const LAS bf16x8*)(lds + PG8_SA(b, h) + aoff + m * 2048 + k * 1024); } while (0)
; #define PG8_LDB(dst, b, h) do { _Pragma("unroll") for (int n = 0; n < 2; ++n) _Pragma("unroll") for (int k = 0; k < 2; ++k) dst[n][k] = *(const LAS bf16x8*)(lds + PG8_SB(b, h) + boff + n * 2048 + k * 1024); } while (0)
; #define PG8_WAIT_V(n) asm volatile("s_waitcnt vmcnt(" #n ")" ::: "memory")
; #define PG8_WAIT_L(n) asm volatile("s_waitcnt lgkmcnt(" #n ")" ::: "memory")
; template <class Epi>
; __device__ __forceinline__ void gemm_phase(LAS unsigned char* lds, const int tid, const Gemm g, const StaticOrder& S, const Epi& E) {
;     ...
;         for (int t = 0; t < nt; t += 2) {
;             const bool last = (t == nt - 2);
;             const char* a1 = cA + (size_t)(t + 1) * kstep;
;             const char* a2 = last ? nA : cA + (size_t)(t + 2) * kstep; const char* b2 = last ? nB : cB + (size_t)(t + 2) * kstep;
;             const char* a3 = a2 + kstep; const char* b3 = b2 + kstep;
;             if constexpr (Epi::SS_LDS) { if (last) {
;                 const char* sp = (const char*)E.ss + (size_t)cur.pm * (256 * 64) + (size_t)tid * 16;
;                 __builtin_amdgcn_global_load_lds((const unsigned*)sp, (LAS unsigned*)(lds + RS_OFF + ldsw), 16, 0, 0);
;                 __builtin_amdgcn_global_load_lds((const unsigned*)(sp + 8192), (LAS unsigned*)(lds + RS_OFF + 8192 + ldsw), 16, 0, 0); } }
;     ...
;             PG8_LDB(B0, 0, 0); PG8_LDB(B1, 0, 1); PG8_SCHED; PG8_LDA(At, 0, 0); PG8_STAGE(PG8_SA(1, 1), a1 + hstepA, voffA);
;             PG8_WAIT_V(8); PG8_WAIT_L(0); PG8_BAR; PG8_MMA(0, 0, At, B0); PG8_MMA(0, 1, At, B1); PG8_BAR; PG8_SCHED;
;             PG8_LDA(At, 0, 1); PG8_STAGE(PG8_SB(0, 0), b2, voffB); PG8_STAGE(PG8_SB(0, 1), b2 + hstepB, voffB); PG8_STAGE(PG8_SA(0, 0), a2, voffA);
;             PG8_WAIT_V(8); PG8_WAIT_L(0); PG8_BAR; PG8_MMA(1, 0, At, B0); PG8_MMA(1, 1, At, B1); PG8_BAR; PG8_SCHED;
.LBB0_442:
	v_add_u32_e32 v136, s61, v171
	ds_read_b128 v[154:157], v136
	ds_read_b128 v[158:161], v136 offset:1024
	ds_read_b128 v[162:165], v136 offset:2048
	ds_read_b128 v[166:169], v136 offset:3072
	v_add_u32_e32 v136, s62, v171
	ds_read_b128 v[176:179], v136
	ds_read_b128 v[180:183], v136 offset:1024
	ds_read_b128 v[184:187], v136 offset:2048
	ds_read_b128 v[188:191], v136 offset:3072
	s_add_i32 s68, s68, 2
	s_add_u32 s40, s36, 0xfffc0080
	s_addc_u32 s41, s37, -1
	s_and_b64 s[38:39], s[38:39], exec
	s_cselect_b32 s41, s4, s41
	s_cselect_b32 s40, s25, s40
	s_cselect_b32 s39, s27, s67
	s_cselect_b32 s38, s66, s35
	v_lshl_add_u64 v[224:225], s[36:37], 0, v[144:145]
	s_add_i32 m0, s50, 0xc000
	ds_read_b128 v[192:195], v173
	ds_read_b128 v[196:199], v173 offset:1024
	ds_read_b128 v[200:203], v173 offset:2048
	ds_read_b128 v[204:207], v173 offset:3072
	ds_read_b128 v[208:211], v173 offset:4096
	ds_read_b128 v[212:215], v173 offset:5120
	ds_read_b128 v[216:219], v173 offset:6144
	ds_read_b128 v[220:223], v173 offset:7168
	global_load_lds_dwordx4 v[224:225], off
	v_lshl_add_u64 v[224:225], s[36:37], 0, v[142:143]
	s_add_i32 m0, s50, 0xe000
	s_nop 0
	global_load_lds_dwordx4 v[224:225], off
	s_waitcnt vmcnt(8)
	s_waitcnt lgkmcnt(0)
	s_barrier
	s_setprio 1
	v_mfma_f32_16x16x32_bf16 v[124:127], v[154:157], v[192:195], v[124:127]
	v_mfma_f32_16x16x32_bf16 v[120:123], v[162:165], v[192:195], v[120:123]
	v_mfma_f32_16x16x32_bf16 v[108:111], v[154:157], v[200:203], v[108:111]
	v_mfma_f32_16x16x32_bf16 v[104:107], v[162:165], v[200:203], v[104:107]
	v_mfma_f32_16x16x32_bf16 v[92:95], v[154:157], v[208:211], v[92:95]
	v_mfma_f32_16x16x32_bf16 v[88:91], v[162:165], v[208:211], v[88:91]
	v_mfma_f32_16x16x32_bf16 v[76:79], v[154:157], v[216:219], v[76:79]
	v_mfma_f32_16x16x32_bf16 v[72:75], v[162:165], v[216:219], v[72:75]
	v_mfma_f32_16x16x32_bf16 v[124:127], v[158:161], v[196:199], v[124:127]
	v_mfma_f32_16x16x32_bf16 v[120:123], v[166:169], v[196:199], v[120:123]
	v_mfma_f32_16x16x32_bf16 v[108:111], v[158:161], v[204:207], v[108:111]
	v_mfma_f32_16x16x32_bf16 v[104:107], v[166:169], v[204:207], v[104:107]
	v_mfma_f32_16x16x32_bf16 v[92:95], v[158:161], v[212:215], v[92:95]
	v_mfma_f32_16x16x32_bf16 v[88:91], v[166:169], v[212:215], v[88:91]
	v_mfma_f32_16x16x32_bf16 v[76:79], v[158:161], v[220:223], v[76:79]
	v_mfma_f32_16x16x32_bf16 v[72:75], v[166:169], v[220:223], v[72:75]
	v_mfma_f32_16x16x32_bf16 v[116:119], v[176:179], v[192:195], v[116:119]
	v_mfma_f32_16x16x32_bf16 v[112:115], v[184:187], v[192:195], v[112:115]
	v_mfma_f32_16x16x32_bf16 v[100:103], v[176:179], v[200:203], v[100:103]
	v_mfma_f32_16x16x32_bf16 v[96:99], v[184:187], v[200:203], v[96:99]
	v_mfma_f32_16x16x32_bf16 v[84:87], v[176:179], v[208:211], v[84:87]
	v_mfma_f32_16x16x32_bf16 v[80:83], v[184:187], v[208:211], v[80:83]
	v_mfma_f32_16x16x32_bf16 v[68:71], v[176:179], v[216:219], v[68:71]
	v_mfma_f32_16x16x32_bf16 v[64:67], v[184:187], v[216:219], v[64:67]
	v_mfma_f32_16x16x32_bf16 v[116:119], v[180:183], v[196:199], v[116:119]
	v_mfma_f32_16x16x32_bf16 v[112:115], v[188:191], v[196:199], v[112:115]
	v_mfma_f32_16x16x32_bf16 v[100:103], v[180:183], v[204:207], v[100:103]
	v_mfma_f32_16x16x32_bf16 v[96:99], v[188:191], v[204:207], v[96:99]
	v_mfma_f32_16x16x32_bf16 v[84:87], v[180:183], v[212:215], v[84:87]
	v_mfma_f32_16x16x32_bf16 v[80:83], v[188:191], v[212:215], v[80:83]
	v_mfma_f32_16x16x32_bf16 v[68:71], v[180:183], v[220:223], v[68:71]
	v_mfma_f32_16x16x32_bf16 v[64:67], v[188:191], v[220:223], v[64:67]
	s_setprio 0
	s_barrier
	s_add_i32 s69, s61, s47
	v_lshl_add_u64 v[224:225], s[38:39], 0, v[132:133]
	s_mov_b32 m0, s69
	ds_read_b128 v[192:195], v173 offset:16384
	ds_read_b128 v[196:199], v173 offset:17408
	ds_read_b128 v[200:203], v173 offset:18432
	ds_read_b128 v[204:207], v173 offset:19456
	ds_read_b128 v[208:211], v173 offset:20480
	ds_read_b128 v[212:215], v173 offset:21504
	ds_read_b128 v[216:219], v173 offset:22528
	ds_read_b128 v[220:223], v173 offset:23552
	global_load_lds_dwordx4 v[224:225], off
	s_add_i32 m0, s69, 0x2000
	s_add_u32 s70, s38, 0x40000
	v_lshl_add_u64 v[226:227], s[38:39], 0, v[128:129]
	s_addc_u32 s71, s39, 0
	s_add_i32 s69, s62, s47
	global_load_lds_dwordx4 v[226:227], off
	v_lshl_add_u64 v[228:229], s[70:71], 0, v[132:133]
	s_mov_b32 m0, s69
	v_lshl_add_u64 v[230:231], s[40:41], 0, v[130:131]
	global_load_lds_dwordx4 v[228:229], off
	v_lshl_add_u64 v[228:229], s[70:71], 0, v[128:129]
	s_add_i32 m0, s69, 0x2000
	s_nop 0
	global_load_lds_dwordx4 v[228:229], off
	v_lshl_add_u64 v[228:229], s[40:41], 0, v[134:135]
	s_mov_b32 m0, s50
	s_nop 0
	global_load_lds_dwordx4 v[228:229], off
	s_mov_b32 m0, s51
	s_nop 0
	global_load_lds_dwordx4 v[230:231], off
	s_waitcnt vmcnt(8)
	s_waitcnt lgkmcnt(0)
	s_barrier
; #define PG8_STAGE(bufoff, gbase, voff) do { _Pragma("unroll") for (int _i = 0; _i < 2; ++_i) \
;         __builtin_amdgcn_global_load_lds((const unsigned*)((const char*)(gbase) + (voff)[_i]), (LAS unsigned*)(lds + (bufoff) + ldsw + _i * 8192), 16, 0, 0); } while (0)
; #define PG8_LDA(dst, b, h) do { _Pragma("unroll") for (int m = 0; m < 4; ++m) _Pragma("unroll") for (int k = 0; k < 2; ++k) dst[m][k] = *(const LAS bf16x8*)(lds + PG8_SA(b, h) + aoff + m * 2048 + k * 1024); } while (0)
; #define PG8_LDB(dst, b, h) do { _Pragma("unroll") for (int n = 0; n < 2; ++n) _Pragma("unroll") for (int k = 0; k < 2; ++k) dst[n][k] = *(const LAS bf16x8*)(lds + PG8_SB(b, h) + boff + n * 2048 + k * 1024); } while (0)
; #define PG8_MMA(ai, bj, At, Bt) do { __builtin_amdgcn_s_setprio(1); _Pragma("unroll") for (int m = 0; m < 4; ++m) _Pragma("unroll") for (int n = 0; n < 2; ++n) _Pragma("unroll") for (int k = 0; k < 2; ++k) \
;         acc[ai][bj][m][n] = __builtin_amdgcn_mfma_f32_16x16x32_bf16(Bt[n][k], At[m][k], acc[ai][bj][m][n], 0, 0, 0); __builtin_amdgcn_s_setprio(0); } while (0)
; #define PG8_WAIT_V(n) asm volatile("s_waitcnt vmcnt(" #n ")" ::: "memory")
; #define PG8_WAIT_L(n) asm volatile("s_waitcnt lgkmcnt(" #n ")" ::: "memory")
; #define PG8_BAR __builtin_amdgcn_s_barrier()
; #define PG8_SCHED __builtin_amdgcn_sched_barrier(0)
; template <class Epi>
; __device__ __forceinline__ void gemm_phase(LAS unsigned char* lds, const int tid, const Gemm g, const StaticOrder& S, const Epi& E) {
;     ...
;             PG8_WAIT_V(8); PG8_WAIT_L(0); PG8_BAR; PG8_MMA(1, 0, At, B0); PG8_MMA(1, 1, At, B1); PG8_BAR; PG8_SCHED;
;             PG8_LDB(B0, 1, 0); PG8_LDB(B1, 1, 1); PG8_SCHED; PG8_LDA(At, 1, 0); PG8_STAGE(PG8_SA(0, 1), a2 + hstepA, voffA);
;             PG8_WAIT_V(8); PG8_WAIT_L(0); PG8_BAR; PG8_MMA(0, 0, At, B0); PG8_MMA(0, 1, At, B1); PG8_BAR; PG8_SCHED;
	s_setprio 1
	v_mfma_f32_16x16x32_bf16 v[60:63], v[154:157], v[192:195], v[60:63]
	v_mfma_f32_16x16x32_bf16 v[56:59], v[162:165], v[192:195], v[56:59]
	v_mfma_f32_16x16x32_bf16 v[44:47], v[154:157], v[200:203], v[44:47]
	v_mfma_f32_16x16x32_bf16 v[40:43], v[162:165], v[200:203], v[40:43]
	v_mfma_f32_16x16x32_bf16 v[28:31], v[154:157], v[208:211], v[28:31]
	v_mfma_f32_16x16x32_bf16 v[24:27], v[162:165], v[208:211], v[24:27]
	v_mfma_f32_16x16x32_bf16 v[12:15], v[154:157], v[216:219], v[12:15]
	v_mfma_f32_16x16x32_bf16 v[8:11], v[162:165], v[216:219], v[8:11]
	v_mfma_f32_16x16x32_bf16 v[60:63], v[158:161], v[196:199], v[60:63]
	v_mfma_f32_16x16x32_bf16 v[56:59], v[166:169], v[196:199], v[56:59]
	v_mfma_f32_16x16x32_bf16 v[44:47], v[158:161], v[204:207], v[44:47]
	v_mfma_f32_16x16x32_bf16 v[40:43], v[166:169], v[204:207], v[40:43]
	v_mfma_f32_16x16x32_bf16 v[28:31], v[158:161], v[212:215], v[28:31]
	v_mfma_f32_16x16x32_bf16 v[24:27], v[166:169], v[212:215], v[24:27]
	v_mfma_f32_16x16x32_bf16 v[12:15], v[158:161], v[220:223], v[12:15]
	v_mfma_f32_16x16x32_bf16 v[8:11], v[166:169], v[220:223], v[8:11]
	v_mfma_f32_16x16x32_bf16 v[52:55], v[176:179], v[192:195], v[52:55]
	v_mfma_f32_16x16x32_bf16 v[48:51], v[184:187], v[192:195], v[48:51]
	v_mfma_f32_16x16x32_bf16 v[36:39], v[176:179], v[200:203], v[36:39]
	v_mfma_f32_16x16x32_bf16 v[32:35], v[184:187], v[200:203], v[32:35]
	v_mfma_f32_16x16x32_bf16 v[20:23], v[176:179], v[208:211], v[20:23]
	v_mfma_f32_16x16x32_bf16 v[16:19], v[184:187], v[208:211], v[16:19]
	v_mfma_f32_16x16x32_bf16 v[4:7], v[176:179], v[216:219], v[4:7]
	v_mfma_f32_16x16x32_bf16 v[0:3], v[184:187], v[216:219], v[0:3]
	v_mfma_f32_16x16x32_bf16 v[52:55], v[180:183], v[196:199], v[52:55]
	v_mfma_f32_16x16x32_bf16 v[48:51], v[188:191], v[196:199], v[48:51]
	v_mfma_f32_16x16x32_bf16 v[36:39], v[180:183], v[204:207], v[36:39]
	v_mfma_f32_16x16x32_bf16 v[32:35], v[188:191], v[204:207], v[32:35]
	v_mfma_f32_16x16x32_bf16 v[20:23], v[180:183], v[212:215], v[20:23]
	v_mfma_f32_16x16x32_bf16 v[16:19], v[188:191], v[212:215], v[16:19]
	v_mfma_f32_16x16x32_bf16 v[4:7], v[180:183], v[220:223], v[4:7]
	v_mfma_f32_16x16x32_bf16 v[0:3], v[188:191], v[220:223], v[0:3]
	s_setprio 0
	s_barrier
	s_add_i32 s69, 0, 0x18000
	v_add_u32_e32 v136, s69, v171
	s_add_i32 s70, 0, 0x1c000
	ds_read_b128 v[154:157], v136
	ds_read_b128 v[158:161], v136 offset:1024
	ds_read_b128 v[162:165], v136 offset:2048
	ds_read_b128 v[166:169], v136 offset:3072
	v_add_u32_e32 v136, s70, v171
	ds_read_b128 v[176:179], v136
	ds_read_b128 v[180:183], v136 offset:1024
	ds_read_b128 v[184:187], v136 offset:2048
	ds_read_b128 v[188:191], v136 offset:3072
	s_add_u32 s40, s40, 0x40000
	s_addc_u32 s41, s41, 0
	s_mov_b32 m0, s52
	v_lshl_add_u64 v[232:233], s[40:41], 0, v[134:135]
	ds_read_b128 v[192:195], v173 offset:32768
	ds_read_b128 v[196:199], v173 offset:33792
	ds_read_b128 v[200:203], v173 offset:34816
	ds_read_b128 v[204:207], v173 offset:35840
	ds_read_b128 v[208:211], v173 offset:36864
	ds_read_b128 v[212:215], v173 offset:37888
	ds_read_b128 v[216:219], v173 offset:38912
	ds_read_b128 v[220:223], v173 offset:39936
	global_load_lds_dwordx4 v[232:233], off
	v_lshl_add_u64 v[232:233], s[40:41], 0, v[130:131]
	s_mov_b32 m0, s53
	s_nop 0
	global_load_lds_dwordx4 v[232:233], off
	s_waitcnt vmcnt(8)
	s_waitcnt lgkmcnt(0)
	s_barrier
	s_setprio 1
	v_mfma_f32_16x16x32_bf16 v[124:127], v[154:157], v[192:195], v[124:127]
	v_mfma_f32_16x16x32_bf16 v[120:123], v[162:165], v[192:195], v[120:123]
	v_mfma_f32_16x16x32_bf16 v[108:111], v[154:157], v[200:203], v[108:111]
	v_mfma_f32_16x16x32_bf16 v[104:107], v[162:165], v[200:203], v[104:107]
	v_mfma_f32_16x16x32_bf16 v[92:95], v[154:157], v[208:211], v[92:95]
	v_mfma_f32_16x16x32_bf16 v[88:91], v[162:165], v[208:211], v[88:91]
	v_mfma_f32_16x16x32_bf16 v[76:79], v[154:157], v[216:219], v[76:79]
	v_mfma_f32_16x16x32_bf16 v[72:75], v[162:165], v[216:219], v[72:75]
	v_mfma_f32_16x16x32_bf16 v[124:127], v[158:161], v[196:199], v[124:127]
	v_mfma_f32_16x16x32_bf16 v[120:123], v[166:169], v[196:199], v[120:123]
	v_mfma_f32_16x16x32_bf16 v[108:111], v[158:161], v[204:207], v[108:111]
	v_mfma_f32_16x16x32_bf16 v[104:107], v[166:169], v[204:207], v[104:107]
	v_mfma_f32_16x16x32_bf16 v[92:95], v[158:161], v[212:215], v[92:95]
	v_mfma_f32_16x16x32_bf16 v[88:91], v[166:169], v[212:215], v[88:91]
	v_mfma_f32_16x16x32_bf16 v[76:79], v[158:161], v[220:223], v[76:79]
	v_mfma_f32_16x16x32_bf16 v[72:75], v[166:169], v[220:223], v[72:75]
	v_mfma_f32_16x16x32_bf16 v[116:119], v[176:179], v[192:195], v[116:119]
	v_mfma_f32_16x16x32_bf16 v[112:115], v[184:187], v[192:195], v[112:115]
	v_mfma_f32_16x16x32_bf16 v[100:103], v[176:179], v[200:203], v[100:103]
	v_mfma_f32_16x16x32_bf16 v[96:99], v[184:187], v[200:203], v[96:99]
	v_mfma_f32_16x16x32_bf16 v[84:87], v[176:179], v[208:211], v[84:87]
	v_mfma_f32_16x16x32_bf16 v[80:83], v[184:187], v[208:211], v[80:83]
	v_mfma_f32_16x16x32_bf16 v[68:71], v[176:179], v[216:219], v[68:71]
	v_mfma_f32_16x16x32_bf16 v[64:67], v[184:187], v[216:219], v[64:67]
	v_mfma_f32_16x16x32_bf16 v[116:119], v[180:183], v[196:199], v[116:119]
	v_mfma_f32_16x16x32_bf16 v[112:115], v[188:191], v[196:199], v[112:115]
	v_mfma_f32_16x16x32_bf16 v[100:103], v[180:183], v[204:207], v[100:103]
	v_mfma_f32_16x16x32_bf16 v[96:99], v[188:191], v[204:207], v[96:99]
	v_mfma_f32_16x16x32_bf16 v[84:87], v[180:183], v[212:215], v[84:87]
	v_mfma_f32_16x16x32_bf16 v[80:83], v[188:191], v[212:215], v[80:83]
	v_mfma_f32_16x16x32_bf16 v[68:71], v[180:183], v[220:223], v[68:71]
	v_mfma_f32_16x16x32_bf16 v[64:67], v[188:191], v[220:223], v[64:67]
	s_setprio 0
	s_barrier
; #define PG8_STAGE(bufoff, gbase, voff) do { _Pragma("unroll") for (int _i = 0; _i < 2; ++_i) \
;         __builtin_amdgcn_global_load_lds((const unsigned*)((const char*)(gbase) + (voff)[_i]), (LAS unsigned*)(lds + (bufoff) + ldsw + _i * 8192), 16, 0, 0); } while (0)
; #define PG8_LDA(dst, b, h) do { _Pragma("unroll") for (int m = 0; m < 4; ++m) _Pragma("unroll") for (int k = 0; k < 2; ++k) dst[m][k] = *(const LAS bf16x8*)(lds + PG8_SA(b, h) + aoff + m * 2048 + k * 1024); } while (0)
; #define PG8_MMA(ai, bj, At, Bt) do { __builtin_amdgcn_s_setprio(1); _Pragma("unroll") for (int m = 0; m < 4; ++m) _Pragma("unroll") for (int n = 0; n < 2; ++n) _Pragma("unroll") for (int k = 0; k < 2; ++k) \
;         acc[ai][bj][m][n] = __builtin_amdgcn_mfma_f32_16x16x32_bf16(Bt[n][k], At[m][k], acc[ai][bj][m][n], 0, 0, 0); __builtin_amdgcn_s_setprio(0); } while (0)
; #define PG8_WAIT_V(n) asm volatile("s_waitcnt vmcnt(" #n ")" ::: "memory")
; #define PG8_WAIT_L(n) asm volatile("s_waitcnt lgkmcnt(" #n ")" ::: "memory")
; #define PG8_BAR __builtin_amdgcn_s_barrier()
; #define PG8_SCHED __builtin_amdgcn_sched_barrier(0)
; template <class Epi>
; __device__ __forceinline__ void gemm_phase(LAS unsigned char* lds, const int tid, const Gemm g, const StaticOrder& S, const Epi& E) {
;     ...
;         for (int t = 0; t < nt; t += 2) {
;             const bool last = (t == nt - 2);
;             const char* a1 = cA + (size_t)(t + 1) * kstep;
;             const char* a2 = last ? nA : cA + (size_t)(t + 2) * kstep; const char* b2 = last ? nB : cB + (size_t)(t + 2) * kstep;
;     ...
;             PG8_LDA(At, 1, 1); PG8_STAGE(PG8_SB(1, 0), b3, voffB); PG8_STAGE(PG8_SB(1, 1), b3 + hstepB, voffB); PG8_STAGE(PG8_SA(1, 0), a3, voffA);
;             PG8_WAIT_V(8); PG8_WAIT_L(0); PG8_BAR; PG8_MMA(1, 0, At, B0); PG8_MMA(1, 1, At, B1); PG8_BAR; PG8_SCHED;
	s_add_i32 s40, s69, s47
	v_lshl_add_u64 v[224:225], v[224:225], 0, s[16:17]
	s_mov_b32 m0, s40
	ds_read_b128 v[192:195], v173 offset:49152
	ds_read_b128 v[196:199], v173 offset:50176
	ds_read_b128 v[200:203], v173 offset:51200
	ds_read_b128 v[204:207], v173 offset:52224
	ds_read_b128 v[208:211], v173 offset:53248
	ds_read_b128 v[212:215], v173 offset:54272
	ds_read_b128 v[216:219], v173 offset:55296
	ds_read_b128 v[220:223], v173 offset:56320
	global_load_lds_dwordx4 v[224:225], off
	s_add_i32 m0, s40, 0x2000
	s_add_u32 s38, s38, 0x40080
	v_lshl_add_u64 v[224:225], v[226:227], 0, s[16:17]
	s_addc_u32 s39, s39, 0
	s_add_i32 s40, s70, s47
	global_load_lds_dwordx4 v[224:225], off
	v_lshl_add_u64 v[224:225], s[38:39], 0, v[132:133]
	s_mov_b32 m0, s40
	s_nop 0
	global_load_lds_dwordx4 v[224:225], off
	v_lshl_add_u64 v[224:225], s[38:39], 0, v[128:129]
	s_add_i32 m0, s40, 0x2000
	s_nop 0
	global_load_lds_dwordx4 v[224:225], off
	v_lshl_add_u64 v[224:225], v[228:229], 0, s[16:17]
	s_mov_b32 m0, s57
	s_nop 0
	global_load_lds_dwordx4 v[224:225], off
	v_lshl_add_u64 v[224:225], v[230:231], 0, s[16:17]
	s_mov_b32 m0, s58
	s_nop 0
	global_load_lds_dwordx4 v[224:225], off
	s_add_u32 s35, s35, 0x100
	s_addc_u32 s67, s67, 0
	s_add_u32 s36, s36, 0x100
	s_addc_u32 s37, s37, 0
	s_cmp_eq_u32 s59, s68
	s_cselect_b64 s[38:39], -1, 0
	s_waitcnt vmcnt(8)
	s_waitcnt lgkmcnt(0)
	s_barrier
	s_setprio 1
	v_mfma_f32_16x16x32_bf16 v[60:63], v[154:157], v[192:195], v[60:63]
	v_mfma_f32_16x16x32_bf16 v[56:59], v[162:165], v[192:195], v[56:59]
	v_mfma_f32_16x16x32_bf16 v[44:47], v[154:157], v[200:203], v[44:47]
	v_mfma_f32_16x16x32_bf16 v[40:43], v[162:165], v[200:203], v[40:43]
	v_mfma_f32_16x16x32_bf16 v[28:31], v[154:157], v[208:211], v[28:31]
	v_mfma_f32_16x16x32_bf16 v[24:27], v[162:165], v[208:211], v[24:27]
	v_mfma_f32_16x16x32_bf16 v[12:15], v[154:157], v[216:219], v[12:15]
	v_mfma_f32_16x16x32_bf16 v[8:11], v[162:165], v[216:219], v[8:11]
	v_mfma_f32_16x16x32_bf16 v[60:63], v[158:161], v[196:199], v[60:63]
	v_mfma_f32_16x16x32_bf16 v[56:59], v[166:169], v[196:199], v[56:59]
	v_mfma_f32_16x16x32_bf16 v[44:47], v[158:161], v[204:207], v[44:47]
	v_mfma_f32_16x16x32_bf16 v[40:43], v[166:169], v[204:207], v[40:43]
	v_mfma_f32_16x16x32_bf16 v[28:31], v[158:161], v[212:215], v[28:31]
	v_mfma_f32_16x16x32_bf16 v[24:27], v[166:169], v[212:215], v[24:27]
	v_mfma_f32_16x16x32_bf16 v[12:15], v[158:161], v[220:223], v[12:15]
	v_mfma_f32_16x16x32_bf16 v[8:11], v[166:169], v[220:223], v[8:11]
	v_mfma_f32_16x16x32_bf16 v[52:55], v[176:179], v[192:195], v[52:55]
	v_mfma_f32_16x16x32_bf16 v[48:51], v[184:187], v[192:195], v[48:51]
	v_mfma_f32_16x16x32_bf16 v[36:39], v[176:179], v[200:203], v[36:39]
	v_mfma_f32_16x16x32_bf16 v[32:35], v[184:187], v[200:203], v[32:35]
	v_mfma_f32_16x16x32_bf16 v[20:23], v[176:179], v[208:211], v[20:23]
	v_mfma_f32_16x16x32_bf16 v[16:19], v[184:187], v[208:211], v[16:19]
	v_mfma_f32_16x16x32_bf16 v[4:7], v[176:179], v[216:219], v[4:7]
	v_mfma_f32_16x16x32_bf16 v[0:3], v[184:187], v[216:219], v[0:3]
	v_mfma_f32_16x16x32_bf16 v[52:55], v[180:183], v[196:199], v[52:55]
	v_mfma_f32_16x16x32_bf16 v[48:51], v[188:191], v[196:199], v[48:51]
	v_mfma_f32_16x16x32_bf16 v[36:39], v[180:183], v[204:207], v[36:39]
	v_mfma_f32_16x16x32_bf16 v[32:35], v[188:191], v[204:207], v[32:35]
	v_mfma_f32_16x16x32_bf16 v[20:23], v[180:183], v[212:215], v[20:23]
	v_mfma_f32_16x16x32_bf16 v[16:19], v[188:191], v[212:215], v[16:19]
	v_mfma_f32_16x16x32_bf16 v[4:7], v[180:183], v[220:223], v[4:7]
	v_mfma_f32_16x16x32_bf16 v[0:3], v[188:191], v[220:223], v[0:3]
	s_setprio 0
	s_barrier
	s_cmp_ge_i32 s68, s55
	s_cbranch_scc1 .LBB0_445
	s_cmp_lg_u32 s59, s68
	s_cbranch_scc1 .LBB0_442
	s_branch .Lrs_2

; #define LAS __attribute__((address_space(3)))
; template <class Epi>
; __device__ __forceinline__ void gemm_phase(LAS unsigned char* lds, const int tid, const Gemm g, const StaticOrder& S, const Epi& E) {
;     ...
;             if constexpr (Epi::SS_LDS) { if (last) {
;                 const char* sp = (const char*)E.ss + (size_t)cur.pm * (256 * 64) + (size_t)tid * 16;
;                 __builtin_amdgcn_global_load_lds((const unsigned*)sp, (LAS unsigned*)(lds + RS_OFF + ldsw), 16, 0, 0);
;                 __builtin_amdgcn_global_load_lds((const unsigned*)(sp + 8192), (LAS unsigned*)(lds + RS_OFF + 8192 + ldsw), 16, 0, 0); } }
.Lrs_2:
	s_add_i32 m0, s50, 0x20800
	s_nop 0
	global_load_lds_dwordx4 v[150:151], off
	s_add_i32 m0, s50, 0x22800
	s_nop 0
	global_load_lds_dwordx4 v[152:153], off
	s_branch .LBB0_442

; #define LAS __attribute__((address_space(3)))
; #define PG8_STAGE(bufoff, gbase, voff) do { _Pragma("unroll") for (int _i = 0; _i < 2; ++_i) \
;         __builtin_amdgcn_global_load_lds((const unsigned*)((const char*)(gbase) + (voff)[_i]), (LAS unsigned*)(lds + (bufoff) + ldsw + _i * 8192), 16, 0, 0); } while (0)
; #define PG8_LDA(dst, b, h) do { _Pragma("unroll") for (int m = 0; m < 4; ++m) _Pragma("unroll") for (int k = 0; k < 2; ++k) dst[m][k] = *(const LAS bf16x8*)(lds + PG8_SA(b, h) + aoff + m * 2048 + k * 1024); } while (0)
; #define PG8_LDB(dst, b, h) do { _Pragma("unroll") for (int n = 0; n < 2; ++n) _Pragma("unroll") for (int k = 0; k < 2; ++k) dst[n][k] = *(const LAS bf16x8*)(lds + PG8_SB(b, h) + boff + n * 2048 + k * 1024); } while (0)
; #define PG8_WAIT_V(n) asm volatile("s_waitcnt vmcnt(" #n ")" ::: "memory")
; #define PG8_WAIT_L(n) asm volatile("s_waitcnt lgkmcnt(" #n ")" ::: "memory")
; template <class Epi>
; __device__ __forceinline__ void gemm_phase(LAS unsigned char* lds, const int tid, const Gemm g, const StaticOrder& S, const Epi& E) {
;     ...
;         for (int t = 0; t < nt; t += 2) {
;             const bool last = (t == nt - 2);
;             const char* a1 = cA + (size_t)(t + 1) * kstep;
;             const char* a2 = last ? nA : cA + (size_t)(t + 2) * kstep; const char* b2 = last ? nB : cB + (size_t)(t + 2) * kstep;
;             const char* a3 = a2 + kstep; const char* b3 = b2 + kstep;
;             if constexpr (Epi::SS_LDS) { if (last) {
;                 const char* sp = (const char*)E.ss + (size_t)cur.pm * (256 * 64) + (size_t)tid * 16;
;                 __builtin_amdgcn_global_load_lds((const unsigned*)sp, (LAS unsigned*)(lds + RS_OFF + ldsw), 16, 0, 0);
;                 __builtin_amdgcn_global_load_lds((const unsigned*)(sp + 8192), (LAS unsigned*)(lds + RS_OFF + 8192 + ldsw), 16, 0, 0); } }
;     ...
;             PG8_LDB(B0, 0, 0); PG8_LDB(B1, 0, 1); PG8_SCHED; PG8_LDA(At, 0, 0); PG8_STAGE(PG8_SA(1, 1), a1 + hstepA, voffA);
;             PG8_WAIT_V(8); PG8_WAIT_L(0); PG8_BAR; PG8_MMA(0, 0, At, B0); PG8_MMA(0, 1, At, B1); PG8_BAR; PG8_SCHED;
;             PG8_LDA(At, 0, 1); PG8_STAGE(PG8_SB(0, 0), b2, voffB); PG8_STAGE(PG8_SB(0, 1), b2 + hstepB, voffB); PG8_STAGE(PG8_SA(0, 0), a2, voffA);
;             PG8_WAIT_V(8); PG8_WAIT_L(0); PG8_BAR; PG8_MMA(1, 0, At, B0); PG8_MMA(1, 1, At, B1); PG8_BAR; PG8_SCHED;
.LBB0_1032:
	v_add_u32_e32 v144, s59, v209
	v_add_u32_e32 v160, s60, v209
	ds_read_b128 v[132:135], v144
	ds_read_b128 v[136:139], v144 offset:1024
	ds_read_b128 v[140:143], v144 offset:2048
	ds_read_b128 v[144:147], v144 offset:3072
	ds_read_b128 v[148:151], v160
	ds_read_b128 v[152:155], v160 offset:1024
	ds_read_b128 v[156:159], v160 offset:2048
	ds_read_b128 v[160:163], v160 offset:3072
	s_add_i32 s64, s64, 2
	s_add_u32 s42, s38, 0xfffc0080
	s_addc_u32 s43, s39, -1
	s_and_b64 s[40:41], s[40:41], exec
	s_cselect_b32 s43, s27, s43
	s_cselect_b32 s42, s29, s42
	s_cselect_b32 s41, s33, s63
	s_cselect_b32 s40, s62, s37
	v_lshl_add_u64 v[206:207], s[38:39], 0, v[192:193]
	s_add_i32 m0, s48, 0xc000
	ds_read_b128 v[164:167], v211
	ds_read_b128 v[168:171], v211 offset:1024
	ds_read_b128 v[172:175], v211 offset:2048
	ds_read_b128 v[176:179], v211 offset:3072
	ds_read_b128 v[198:201], v211 offset:4096
	ds_read_b128 v[202:205], v211 offset:5120
	ds_read_b128 v[214:217], v211 offset:6144
	ds_read_b128 v[218:221], v211 offset:7168
	global_load_lds_dwordx4 v[206:207], off
	v_lshl_add_u64 v[206:207], s[38:39], 0, v[190:191]
	s_add_i32 m0, s48, 0xe000
	s_nop 0
	global_load_lds_dwordx4 v[206:207], off
	s_waitcnt vmcnt(8)
	s_waitcnt lgkmcnt(0)
	s_barrier
	s_setprio 1
	v_mfma_f32_16x16x32_bf16 v[124:127], v[132:135], v[164:167], v[124:127]
	v_mfma_f32_16x16x32_bf16 v[120:123], v[140:143], v[164:167], v[120:123]
	v_mfma_f32_16x16x32_bf16 v[108:111], v[132:135], v[172:175], v[108:111]
	v_mfma_f32_16x16x32_bf16 v[104:107], v[140:143], v[172:175], v[104:107]
	v_mfma_f32_16x16x32_bf16 v[92:95], v[132:135], v[198:201], v[92:95]
	v_mfma_f32_16x16x32_bf16 v[88:91], v[140:143], v[198:201], v[88:91]
	v_mfma_f32_16x16x32_bf16 v[76:79], v[132:135], v[214:217], v[76:79]
	v_mfma_f32_16x16x32_bf16 v[72:75], v[140:143], v[214:217], v[72:75]
	v_mfma_f32_16x16x32_bf16 v[124:127], v[136:139], v[168:171], v[124:127]
	v_mfma_f32_16x16x32_bf16 v[120:123], v[144:147], v[168:171], v[120:123]
	v_mfma_f32_16x16x32_bf16 v[108:111], v[136:139], v[176:179], v[108:111]
	v_mfma_f32_16x16x32_bf16 v[104:107], v[144:147], v[176:179], v[104:107]
	v_mfma_f32_16x16x32_bf16 v[92:95], v[136:139], v[202:205], v[92:95]
	v_mfma_f32_16x16x32_bf16 v[88:91], v[144:147], v[202:205], v[88:91]
	v_mfma_f32_16x16x32_bf16 v[76:79], v[136:139], v[218:221], v[76:79]
	v_mfma_f32_16x16x32_bf16 v[72:75], v[144:147], v[218:221], v[72:75]
	v_mfma_f32_16x16x32_bf16 v[116:119], v[148:151], v[164:167], v[116:119]
	v_mfma_f32_16x16x32_bf16 v[112:115], v[156:159], v[164:167], v[112:115]
	v_mfma_f32_16x16x32_bf16 v[100:103], v[148:151], v[172:175], v[100:103]
	v_mfma_f32_16x16x32_bf16 v[96:99], v[156:159], v[172:175], v[96:99]
	v_mfma_f32_16x16x32_bf16 v[84:87], v[148:151], v[198:201], v[84:87]
	v_mfma_f32_16x16x32_bf16 v[80:83], v[156:159], v[198:201], v[80:83]
	v_mfma_f32_16x16x32_bf16 v[68:71], v[148:151], v[214:217], v[68:71]
	v_mfma_f32_16x16x32_bf16 v[64:67], v[156:159], v[214:217], v[64:67]
	v_mfma_f32_16x16x32_bf16 v[116:119], v[152:155], v[168:171], v[116:119]
	v_mfma_f32_16x16x32_bf16 v[112:115], v[160:163], v[168:171], v[112:115]
	v_mfma_f32_16x16x32_bf16 v[100:103], v[152:155], v[176:179], v[100:103]
	v_mfma_f32_16x16x32_bf16 v[96:99], v[160:163], v[176:179], v[96:99]
	v_mfma_f32_16x16x32_bf16 v[84:87], v[152:155], v[202:205], v[84:87]
	v_mfma_f32_16x16x32_bf16 v[80:83], v[160:163], v[202:205], v[80:83]
	v_mfma_f32_16x16x32_bf16 v[68:71], v[152:155], v[218:221], v[68:71]
	v_mfma_f32_16x16x32_bf16 v[64:67], v[160:163], v[218:221], v[64:67]
	s_setprio 0
	s_barrier
	s_add_i32 s65, s59, s47
	v_lshl_add_u64 v[206:207], s[40:41], 0, v[182:183]
	s_mov_b32 m0, s65
	ds_read_b128 v[164:167], v211 offset:16384
	ds_read_b128 v[168:171], v211 offset:17408
	ds_read_b128 v[172:175], v211 offset:18432
	ds_read_b128 v[176:179], v211 offset:19456
	ds_read_b128 v[198:201], v211 offset:20480
	ds_read_b128 v[202:205], v211 offset:21504
	ds_read_b128 v[214:217], v211 offset:22528
	ds_read_b128 v[218:221], v211 offset:23552
	global_load_lds_dwordx4 v[206:207], off
	s_add_i32 m0, s65, 0x2000
	s_add_u32 s66, s40, 0x40000
	v_lshl_add_u64 v[222:223], s[40:41], 0, v[186:187]
	s_addc_u32 s67, s41, 0
	s_add_i32 s65, s60, s47
	global_load_lds_dwordx4 v[222:223], off
	v_lshl_add_u64 v[224:225], s[66:67], 0, v[182:183]
	s_mov_b32 m0, s65
	v_lshl_add_u64 v[226:227], s[42:43], 0, v[184:185]
	global_load_lds_dwordx4 v[224:225], off
	v_lshl_add_u64 v[224:225], s[66:67], 0, v[186:187]
	s_add_i32 m0, s65, 0x2000
	s_nop 0
	global_load_lds_dwordx4 v[224:225], off
	v_lshl_add_u64 v[224:225], s[42:43], 0, v[180:181]
	s_mov_b32 m0, s48
	s_nop 0
	global_load_lds_dwordx4 v[224:225], off
	s_mov_b32 m0, s49
	s_nop 0
	global_load_lds_dwordx4 v[226:227], off
	s_waitcnt vmcnt(8)
	s_waitcnt lgkmcnt(0)
	s_barrier
; #define PG8_STAGE(bufoff, gbase, voff) do { _Pragma("unroll") for (int _i = 0; _i < 2; ++_i) \
;         __builtin_amdgcn_global_load_lds((const unsigned*)((const char*)(gbase) + (voff)[_i]), (LAS unsigned*)(lds + (bufoff) + ldsw + _i * 8192), 16, 0, 0); } while (0)
; #define PG8_LDA(dst, b, h) do { _Pragma("unroll") for (int m = 0; m < 4; ++m) _Pragma("unroll") for (int k = 0; k < 2; ++k) dst[m][k] = *(const LAS bf16x8*)(lds + PG8_SA(b, h) + aoff + m * 2048 + k * 1024); } while (0)
; #define PG8_LDB(dst, b, h) do { _Pragma("unroll") for (int n = 0; n < 2; ++n) _Pragma("unroll") for (int k = 0; k < 2; ++k) dst[n][k] = *(const LAS bf16x8*)(lds + PG8_SB(b, h) + boff + n * 2048 + k * 1024); } while (0)
; #define PG8_MMA(ai, bj, At, Bt) do { __builtin_amdgcn_s_setprio(1); _Pragma("unroll") for (int m = 0; m < 4; ++m) _Pragma("unroll") for (int n = 0; n < 2; ++n) _Pragma("unroll") for (int k = 0; k < 2; ++k) \
;         acc[ai][bj][m][n] = __builtin_amdgcn_mfma_f32_16x16x32_bf16(Bt[n][k], At[m][k], acc[ai][bj][m][n], 0, 0, 0); __builtin_amdgcn_s_setprio(0); } while (0)
; #define PG8_WAIT_V(n) asm volatile("s_waitcnt vmcnt(" #n ")" ::: "memory")
; #define PG8_WAIT_L(n) asm volatile("s_waitcnt lgkmcnt(" #n ")" ::: "memory")
; #define PG8_BAR __builtin_amdgcn_s_barrier()
; #define PG8_SCHED __builtin_amdgcn_sched_barrier(0)
; template <class Epi>
; __device__ __forceinline__ void gemm_phase(LAS unsigned char* lds, const int tid, const Gemm g, const StaticOrder& S, const Epi& E) {
;     ...
;             PG8_WAIT_V(8); PG8_WAIT_L(0); PG8_BAR; PG8_MMA(1, 0, At, B0); PG8_MMA(1, 1, At, B1); PG8_BAR; PG8_SCHED;
;             PG8_LDB(B0, 1, 0); PG8_LDB(B1, 1, 1); PG8_SCHED; PG8_LDA(At, 1, 0); PG8_STAGE(PG8_SA(0, 1), a2 + hstepA, voffA);
;             PG8_WAIT_V(8); PG8_WAIT_L(0); PG8_BAR; PG8_MMA(0, 0, At, B0); PG8_MMA(0, 1, At, B1); PG8_BAR; PG8_SCHED;
	s_setprio 1
	v_mfma_f32_16x16x32_bf16 v[60:63], v[132:135], v[164:167], v[60:63]
	v_mfma_f32_16x16x32_bf16 v[56:59], v[140:143], v[164:167], v[56:59]
	v_mfma_f32_16x16x32_bf16 v[44:47], v[132:135], v[172:175], v[44:47]
	v_mfma_f32_16x16x32_bf16 v[40:43], v[140:143], v[172:175], v[40:43]
	v_mfma_f32_16x16x32_bf16 v[28:31], v[132:135], v[198:201], v[28:31]
	v_mfma_f32_16x16x32_bf16 v[24:27], v[140:143], v[198:201], v[24:27]
	v_mfma_f32_16x16x32_bf16 v[12:15], v[132:135], v[214:217], v[12:15]
	v_mfma_f32_16x16x32_bf16 v[8:11], v[140:143], v[214:217], v[8:11]
	v_mfma_f32_16x16x32_bf16 v[60:63], v[136:139], v[168:171], v[60:63]
	v_mfma_f32_16x16x32_bf16 v[56:59], v[144:147], v[168:171], v[56:59]
	v_mfma_f32_16x16x32_bf16 v[44:47], v[136:139], v[176:179], v[44:47]
	v_mfma_f32_16x16x32_bf16 v[40:43], v[144:147], v[176:179], v[40:43]
	v_mfma_f32_16x16x32_bf16 v[28:31], v[136:139], v[202:205], v[28:31]
	v_mfma_f32_16x16x32_bf16 v[24:27], v[144:147], v[202:205], v[24:27]
	v_mfma_f32_16x16x32_bf16 v[12:15], v[136:139], v[218:221], v[12:15]
	v_mfma_f32_16x16x32_bf16 v[8:11], v[144:147], v[218:221], v[8:11]
	v_mfma_f32_16x16x32_bf16 v[52:55], v[148:151], v[164:167], v[52:55]
	v_mfma_f32_16x16x32_bf16 v[48:51], v[156:159], v[164:167], v[48:51]
	v_mfma_f32_16x16x32_bf16 v[36:39], v[148:151], v[172:175], v[36:39]
	v_mfma_f32_16x16x32_bf16 v[32:35], v[156:159], v[172:175], v[32:35]
	v_mfma_f32_16x16x32_bf16 v[20:23], v[148:151], v[198:201], v[20:23]
	v_mfma_f32_16x16x32_bf16 v[16:19], v[156:159], v[198:201], v[16:19]
	v_mfma_f32_16x16x32_bf16 v[4:7], v[148:151], v[214:217], v[4:7]
	v_mfma_f32_16x16x32_bf16 v[0:3], v[156:159], v[214:217], v[0:3]
	v_mfma_f32_16x16x32_bf16 v[52:55], v[152:155], v[168:171], v[52:55]
	v_mfma_f32_16x16x32_bf16 v[48:51], v[160:163], v[168:171], v[48:51]
	v_mfma_f32_16x16x32_bf16 v[36:39], v[152:155], v[176:179], v[36:39]
	v_mfma_f32_16x16x32_bf16 v[32:35], v[160:163], v[176:179], v[32:35]
	v_mfma_f32_16x16x32_bf16 v[20:23], v[152:155], v[202:205], v[20:23]
	v_mfma_f32_16x16x32_bf16 v[16:19], v[160:163], v[202:205], v[16:19]
	v_mfma_f32_16x16x32_bf16 v[4:7], v[152:155], v[218:221], v[4:7]
	v_mfma_f32_16x16x32_bf16 v[0:3], v[160:163], v[218:221], v[0:3]
	s_setprio 0
	s_barrier
	s_add_i32 s65, 0, 0x18000
	s_add_i32 s66, 0, 0x1c000
	v_add_u32_e32 v144, s65, v209
	v_add_u32_e32 v160, s66, v209
	ds_read_b128 v[132:135], v144
	ds_read_b128 v[136:139], v144 offset:1024
	ds_read_b128 v[140:143], v144 offset:2048
	ds_read_b128 v[144:147], v144 offset:3072
	ds_read_b128 v[148:151], v160
	ds_read_b128 v[152:155], v160 offset:1024
	ds_read_b128 v[156:159], v160 offset:2048
	ds_read_b128 v[160:163], v160 offset:3072
	s_add_u32 s42, s42, 0x40000
	s_addc_u32 s43, s43, 0
	s_mov_b32 m0, s50
	v_lshl_add_u64 v[228:229], s[42:43], 0, v[180:181]
	ds_read_b128 v[164:167], v211 offset:32768
	ds_read_b128 v[168:171], v211 offset:33792
	ds_read_b128 v[172:175], v211 offset:34816
	ds_read_b128 v[176:179], v211 offset:35840
	ds_read_b128 v[198:201], v211 offset:36864
	ds_read_b128 v[202:205], v211 offset:37888
	ds_read_b128 v[214:217], v211 offset:38912
	ds_read_b128 v[218:221], v211 offset:39936
	global_load_lds_dwordx4 v[228:229], off
	v_lshl_add_u64 v[228:229], s[42:43], 0, v[184:185]
	s_mov_b32 m0, s51
	s_nop 0
	global_load_lds_dwordx4 v[228:229], off
	s_waitcnt vmcnt(8)
	s_waitcnt lgkmcnt(0)
	s_barrier
	s_setprio 1
	v_mfma_f32_16x16x32_bf16 v[124:127], v[132:135], v[164:167], v[124:127]
	v_mfma_f32_16x16x32_bf16 v[120:123], v[140:143], v[164:167], v[120:123]
	v_mfma_f32_16x16x32_bf16 v[108:111], v[132:135], v[172:175], v[108:111]
	v_mfma_f32_16x16x32_bf16 v[104:107], v[140:143], v[172:175], v[104:107]
	v_mfma_f32_16x16x32_bf16 v[92:95], v[132:135], v[198:201], v[92:95]
	v_mfma_f32_16x16x32_bf16 v[88:91], v[140:143], v[198:201], v[88:91]
	v_mfma_f32_16x16x32_bf16 v[76:79], v[132:135], v[214:217], v[76:79]
	v_mfma_f32_16x16x32_bf16 v[72:75], v[140:143], v[214:217], v[72:75]
	v_mfma_f32_16x16x32_bf16 v[124:127], v[136:139], v[168:171], v[124:127]
	v_mfma_f32_16x16x32_bf16 v[120:123], v[144:147], v[168:171], v[120:123]
	v_mfma_f32_16x16x32_bf16 v[108:111], v[136:139], v[176:179], v[108:111]
	v_mfma_f32_16x16x32_bf16 v[104:107], v[144:147], v[176:179], v[104:107]
	v_mfma_f32_16x16x32_bf16 v[92:95], v[136:139], v[202:205], v[92:95]
	v_mfma_f32_16x16x32_bf16 v[88:91], v[144:147], v[202:205], v[88:91]
	v_mfma_f32_16x16x32_bf16 v[76:79], v[136:139], v[218:221], v[76:79]
	v_mfma_f32_16x16x32_bf16 v[72:75], v[144:147], v[218:221], v[72:75]
	v_mfma_f32_16x16x32_bf16 v[116:119], v[148:151], v[164:167], v[116:119]
	v_mfma_f32_16x16x32_bf16 v[112:115], v[156:159], v[164:167], v[112:115]
	v_mfma_f32_16x16x32_bf16 v[100:103], v[148:151], v[172:175], v[100:103]
	v_mfma_f32_16x16x32_bf16 v[96:99], v[156:159], v[172:175], v[96:99]
	v_mfma_f32_16x16x32_bf16 v[84:87], v[148:151], v[198:201], v[84:87]
	v_mfma_f32_16x16x32_bf16 v[80:83], v[156:159], v[198:201], v[80:83]
	v_mfma_f32_16x16x32_bf16 v[68:71], v[148:151], v[214:217], v[68:71]
	v_mfma_f32_16x16x32_bf16 v[64:67], v[156:159], v[214:217], v[64:67]
	v_mfma_f32_16x16x32_bf16 v[116:119], v[152:155], v[168:171], v[116:119]
	v_mfma_f32_16x16x32_bf16 v[112:115], v[160:163], v[168:171], v[112:115]
	v_mfma_f32_16x16x32_bf16 v[100:103], v[152:155], v[176:179], v[100:103]
	v_mfma_f32_16x16x32_bf16 v[96:99], v[160:163], v[176:179], v[96:99]
	v_mfma_f32_16x16x32_bf16 v[84:87], v[152:155], v[202:205], v[84:87]
	v_mfma_f32_16x16x32_bf16 v[80:83], v[160:163], v[202:205], v[80:83]
	v_mfma_f32_16x16x32_bf16 v[68:71], v[152:155], v[218:221], v[68:71]
	v_mfma_f32_16x16x32_bf16 v[64:67], v[160:163], v[218:221], v[64:67]
	s_setprio 0
	s_barrier
; #define PG8_STAGE(bufoff, gbase, voff) do { _Pragma("unroll") for (int _i = 0; _i < 2; ++_i) \
;         __builtin_amdgcn_global_load_lds((const unsigned*)((const char*)(gbase) + (voff)[_i]), (LAS unsigned*)(lds + (bufoff) + ldsw + _i * 8192), 16, 0, 0); } while (0)
; #define PG8_LDA(dst, b, h) do { _Pragma("unroll") for (int m = 0; m < 4; ++m) _Pragma("unroll") for (int k = 0; k < 2; ++k) dst[m][k] = *(const LAS bf16x8*)(lds + PG8_SA(b, h) + aoff + m * 2048 + k * 1024); } while (0)
; #define PG8_MMA(ai, bj, At, Bt) do { __builtin_amdgcn_s_setprio(1); _Pragma("unroll") for (int m = 0; m < 4; ++m) _Pragma("unroll") for (int n = 0; n < 2; ++n) _Pragma("unroll") for (int k = 0; k < 2; ++k) \
;         acc[ai][bj][m][n] = __builtin_amdgcn_mfma_f32_16x16x32_bf16(Bt[n][k], At[m][k], acc[ai][bj][m][n], 0, 0, 0); __builtin_amdgcn_s_setprio(0); } while (0)
; #define PG8_WAIT_V(n) asm volatile("s_waitcnt vmcnt(" #n ")" ::: "memory")
; #define PG8_WAIT_L(n) asm volatile("s_waitcnt lgkmcnt(" #n ")" ::: "memory")
; #define PG8_BAR __builtin_amdgcn_s_barrier()
; #define PG8_SCHED __builtin_amdgcn_sched_barrier(0)
; template <class Epi>
; __device__ __forceinline__ void gemm_phase(LAS unsigned char* lds, const int tid, const Gemm g, const StaticOrder& S, const Epi& E) {
;     ...
;         for (int t = 0; t < nt; t += 2) {
;             const bool last = (t == nt - 2);
;             const char* a1 = cA + (size_t)(t + 1) * kstep;
;             const char* a2 = last ? nA : cA + (size_t)(t + 2) * kstep; const char* b2 = last ? nB : cB + (size_t)(t + 2) * kstep;
;     ...
;             PG8_LDA(At, 1, 1); PG8_STAGE(PG8_SB(1, 0), b3, voffB); PG8_STAGE(PG8_SB(1, 1), b3 + hstepB, voffB); PG8_STAGE(PG8_SA(1, 0), a3, voffA);
;             PG8_WAIT_V(8); PG8_WAIT_L(0); PG8_BAR; PG8_MMA(1, 0, At, B0); PG8_MMA(1, 1, At, B1); PG8_BAR; PG8_SCHED;
	s_add_i32 s42, s65, s47
	v_lshl_add_u64 v[206:207], v[206:207], 0, s[20:21]
	s_mov_b32 m0, s42
	ds_read_b128 v[164:167], v211 offset:49152
	ds_read_b128 v[168:171], v211 offset:50176
	ds_read_b128 v[172:175], v211 offset:51200
	ds_read_b128 v[176:179], v211 offset:52224
	ds_read_b128 v[198:201], v211 offset:53248
	ds_read_b128 v[202:205], v211 offset:54272
	ds_read_b128 v[214:217], v211 offset:55296
	ds_read_b128 v[218:221], v211 offset:56320
	global_load_lds_dwordx4 v[206:207], off
	s_add_i32 m0, s42, 0x2000
	s_add_u32 s40, s40, 0x40080
	v_lshl_add_u64 v[206:207], v[222:223], 0, s[20:21]
	s_addc_u32 s41, s41, 0
	s_add_i32 s42, s66, s47
	global_load_lds_dwordx4 v[206:207], off
	v_lshl_add_u64 v[206:207], s[40:41], 0, v[182:183]
	s_mov_b32 m0, s42
	s_nop 0
	global_load_lds_dwordx4 v[206:207], off
	v_lshl_add_u64 v[206:207], s[40:41], 0, v[186:187]
	s_add_i32 m0, s42, 0x2000
	s_nop 0
	global_load_lds_dwordx4 v[206:207], off
	v_lshl_add_u64 v[206:207], v[224:225], 0, s[20:21]
	s_mov_b32 m0, s54
	s_nop 0
	global_load_lds_dwordx4 v[206:207], off
	v_lshl_add_u64 v[206:207], v[226:227], 0, s[20:21]
	s_mov_b32 m0, s55
	s_nop 0
	global_load_lds_dwordx4 v[206:207], off
	s_add_u32 s37, s37, 0x100
	s_addc_u32 s63, s63, 0
	s_add_u32 s38, s38, 0x100
	s_addc_u32 s39, s39, 0
	s_cmp_eq_u32 s56, s64
	s_cselect_b64 s[40:41], -1, 0
	s_waitcnt vmcnt(8)
	s_waitcnt lgkmcnt(0)
	s_barrier
	s_setprio 1
	v_mfma_f32_16x16x32_bf16 v[60:63], v[132:135], v[164:167], v[60:63]
	v_mfma_f32_16x16x32_bf16 v[56:59], v[140:143], v[164:167], v[56:59]
	v_mfma_f32_16x16x32_bf16 v[44:47], v[132:135], v[172:175], v[44:47]
	v_mfma_f32_16x16x32_bf16 v[40:43], v[140:143], v[172:175], v[40:43]
	v_mfma_f32_16x16x32_bf16 v[28:31], v[132:135], v[198:201], v[28:31]
	v_mfma_f32_16x16x32_bf16 v[24:27], v[140:143], v[198:201], v[24:27]
	v_mfma_f32_16x16x32_bf16 v[12:15], v[132:135], v[214:217], v[12:15]
	v_mfma_f32_16x16x32_bf16 v[8:11], v[140:143], v[214:217], v[8:11]
	v_mfma_f32_16x16x32_bf16 v[60:63], v[136:139], v[168:171], v[60:63]
	v_mfma_f32_16x16x32_bf16 v[56:59], v[144:147], v[168:171], v[56:59]
	v_mfma_f32_16x16x32_bf16 v[44:47], v[136:139], v[176:179], v[44:47]
	v_mfma_f32_16x16x32_bf16 v[40:43], v[144:147], v[176:179], v[40:43]
	v_mfma_f32_16x16x32_bf16 v[28:31], v[136:139], v[202:205], v[28:31]
	v_mfma_f32_16x16x32_bf16 v[24:27], v[144:147], v[202:205], v[24:27]
	v_mfma_f32_16x16x32_bf16 v[12:15], v[136:139], v[218:221], v[12:15]
	v_mfma_f32_16x16x32_bf16 v[8:11], v[144:147], v[218:221], v[8:11]
	v_mfma_f32_16x16x32_bf16 v[52:55], v[148:151], v[164:167], v[52:55]
	v_mfma_f32_16x16x32_bf16 v[48:51], v[156:159], v[164:167], v[48:51]
	v_mfma_f32_16x16x32_bf16 v[36:39], v[148:151], v[172:175], v[36:39]
	v_mfma_f32_16x16x32_bf16 v[32:35], v[156:159], v[172:175], v[32:35]
	v_mfma_f32_16x16x32_bf16 v[20:23], v[148:151], v[198:201], v[20:23]
	v_mfma_f32_16x16x32_bf16 v[16:19], v[156:159], v[198:201], v[16:19]
	v_mfma_f32_16x16x32_bf16 v[4:7], v[148:151], v[214:217], v[4:7]
	v_mfma_f32_16x16x32_bf16 v[0:3], v[156:159], v[214:217], v[0:3]
	v_mfma_f32_16x16x32_bf16 v[52:55], v[152:155], v[168:171], v[52:55]
	v_mfma_f32_16x16x32_bf16 v[48:51], v[160:163], v[168:171], v[48:51]
	v_mfma_f32_16x16x32_bf16 v[36:39], v[152:155], v[176:179], v[36:39]
	v_mfma_f32_16x16x32_bf16 v[32:35], v[160:163], v[176:179], v[32:35]
	v_mfma_f32_16x16x32_bf16 v[20:23], v[152:155], v[202:205], v[20:23]
	v_mfma_f32_16x16x32_bf16 v[16:19], v[160:163], v[202:205], v[16:19]
	v_mfma_f32_16x16x32_bf16 v[4:7], v[152:155], v[218:221], v[4:7]
	v_mfma_f32_16x16x32_bf16 v[0:3], v[160:163], v[218:221], v[0:3]
	s_setprio 0
	s_barrier
	s_cmp_ge_i32 s64, s53
	s_cbranch_scc1 .LBB0_1035
	s_cmp_lg_u32 s56, s64
	s_cbranch_scc1 .LBB0_1032
	s_branch .Lrs_4

; #define LAS __attribute__((address_space(3)))
; template <class Epi>
; __device__ __forceinline__ void gemm_phase(LAS unsigned char* lds, const int tid, const Gemm g, const StaticOrder& S, const Epi& E) {
;     ...
;             if constexpr (Epi::SS_LDS) { if (last) {
;                 const char* sp = (const char*)E.ss + (size_t)cur.pm * (256 * 64) + (size_t)tid * 16;
;                 __builtin_amdgcn_global_load_lds((const unsigned*)sp, (LAS unsigned*)(lds + RS_OFF + ldsw), 16, 0, 0);
;                 __builtin_amdgcn_global_load_lds((const unsigned*)(sp + 8192), (LAS unsigned*)(lds + RS_OFF + 8192 + ldsw), 16, 0, 0); } }
.Lrs_4:
	s_add_i32 m0, s48, 0x20800
	s_nop 0
	global_load_lds_dwordx4 v[128:129], off
	s_add_i32 m0, s48, 0x22800
	s_nop 0
	global_load_lds_dwordx4 v[130:131], off
	s_branch .LBB0_1032

; #define LAS __attribute__((address_space(3)))
; #define PG8_STAGE(bufoff, gbase, voff) do { _Pragma("unroll") for (int _i = 0; _i < 2; ++_i) \
;         __builtin_amdgcn_global_load_lds((const unsigned*)((const char*)(gbase) + (voff)[_i]), (LAS unsigned*)(lds + (bufoff) + ldsw + _i * 8192), 16, 0, 0); } while (0)
; #define PG8_LDA(dst, b, h) do { _Pragma("unroll") for (int m = 0; m < 4; ++m) _Pragma("unroll") for (int k = 0; k < 2; ++k) dst[m][k] = *(const LAS bf16x8*)(lds + PG8_SA(b, h) + aoff + m * 2048 + k * 1024); } while (0)
; #define PG8_LDB(dst, b, h) do { _Pragma("unroll") for (int n = 0; n < 2; ++n) _Pragma("unroll") for (int k = 0; k < 2; ++k) dst[n][k] = *(const LAS bf16x8*)(lds + PG8_SB(b, h) + boff + n * 2048 + k * 1024); } while (0)
; #define PG8_WAIT_V(n) asm volatile("s_waitcnt vmcnt(" #n ")" ::: "memory")
; #define PG8_WAIT_L(n) asm volatile("s_waitcnt lgkmcnt(" #n ")" ::: "memory")
; template <class Epi>
; __device__ __forceinline__ void gemm_phase(LAS unsigned char* lds, const int tid, const Gemm g, const StaticOrder& S, const Epi& E) {
;     ...
;         for (int t = 0; t < nt; t += 2) {
;             const bool last = (t == nt - 2);
;             const char* a1 = cA + (size_t)(t + 1) * kstep;
;             const char* a2 = last ? nA : cA + (size_t)(t + 2) * kstep; const char* b2 = last ? nB : cB + (size_t)(t + 2) * kstep;
;             const char* a3 = a2 + kstep; const char* b3 = b2 + kstep;
;             if constexpr (Epi::SS_LDS) { if (last) {
;                 const char* sp = (const char*)E.ss + (size_t)cur.pm * (256 * 64) + (size_t)tid * 16;
;                 __builtin_amdgcn_global_load_lds((const unsigned*)sp, (LAS unsigned*)(lds + RS_OFF + ldsw), 16, 0, 0);
;                 __builtin_amdgcn_global_load_lds((const unsigned*)(sp + 8192), (LAS unsigned*)(lds + RS_OFF + 8192 + ldsw), 16, 0, 0); } }
;     ...
;             PG8_LDB(B0, 0, 0); PG8_LDB(B1, 0, 1); PG8_SCHED; PG8_LDA(At, 0, 0); PG8_STAGE(PG8_SA(1, 1), a1 + hstepA, voffA);
;             PG8_WAIT_V(8); PG8_WAIT_L(0); PG8_BAR; PG8_MMA(0, 0, At, B0); PG8_MMA(0, 1, At, B1); PG8_BAR; PG8_SCHED;
;             PG8_LDA(At, 0, 1); PG8_STAGE(PG8_SB(0, 0), b2, voffB); PG8_STAGE(PG8_SB(0, 1), b2 + hstepB, voffB); PG8_STAGE(PG8_SA(0, 0), a2, voffA);
;             PG8_WAIT_V(8); PG8_WAIT_L(0); PG8_BAR; PG8_MMA(1, 0, At, B0); PG8_MMA(1, 1, At, B1); PG8_BAR; PG8_SCHED;
.LBB0_1312:
	v_add_u32_e32 v161, s52, v157
	ds_read_b128 v[152:155], v161
	ds_read_b128 v[162:165], v161 offset:1024
	ds_read_b128 v[166:169], v161 offset:2048
	ds_read_b128 v[170:173], v161 offset:3072
	v_add_u32_e32 v161, s53, v157
	ds_read_b128 v[174:177], v161
	ds_read_b128 v[178:181], v161 offset:1024
	ds_read_b128 v[182:185], v161 offset:2048
	ds_read_b128 v[186:189], v161 offset:3072
	s_add_i32 s58, s58, 2
	s_add_u32 s34, s28, 0xfffc0080
	s_addc_u32 s35, s29, -1
	s_and_b64 s[30:31], s[30:31], exec
	s_cselect_b32 s35, s19, s35
	s_cselect_b32 s34, s21, s34
	s_cselect_b32 s31, s33, s57
	s_cselect_b32 s30, s56, s5
	v_lshl_add_u64 v[222:223], s[28:29], 0, v[142:143]
	s_add_i32 m0, s27, 0xc000
	ds_read_b128 v[190:193], v158
	ds_read_b128 v[194:197], v158 offset:1024
	ds_read_b128 v[198:201], v158 offset:2048
	ds_read_b128 v[202:205], v158 offset:3072
	ds_read_b128 v[206:209], v158 offset:4096
	ds_read_b128 v[210:213], v158 offset:5120
	ds_read_b128 v[214:217], v158 offset:6144
	ds_read_b128 v[218:221], v158 offset:7168
	global_load_lds_dwordx4 v[222:223], off
	v_lshl_add_u64 v[222:223], s[28:29], 0, v[140:141]
	s_add_i32 m0, s27, 0xe000
	s_nop 0
	global_load_lds_dwordx4 v[222:223], off
	s_waitcnt vmcnt(8)
	s_waitcnt lgkmcnt(0)
	s_barrier
	s_setprio 1
	v_mfma_f32_16x16x32_bf16 v[124:127], v[152:155], v[190:193], v[124:127]
	v_mfma_f32_16x16x32_bf16 v[120:123], v[166:169], v[190:193], v[120:123]
	v_mfma_f32_16x16x32_bf16 v[108:111], v[152:155], v[198:201], v[108:111]
	v_mfma_f32_16x16x32_bf16 v[104:107], v[166:169], v[198:201], v[104:107]
	v_mfma_f32_16x16x32_bf16 v[92:95], v[152:155], v[206:209], v[92:95]
	v_mfma_f32_16x16x32_bf16 v[88:91], v[166:169], v[206:209], v[88:91]
	v_mfma_f32_16x16x32_bf16 v[76:79], v[152:155], v[214:217], v[76:79]
	v_mfma_f32_16x16x32_bf16 v[72:75], v[166:169], v[214:217], v[72:75]
	v_mfma_f32_16x16x32_bf16 v[124:127], v[162:165], v[194:197], v[124:127]
	v_mfma_f32_16x16x32_bf16 v[120:123], v[170:173], v[194:197], v[120:123]
	v_mfma_f32_16x16x32_bf16 v[108:111], v[162:165], v[202:205], v[108:111]
	v_mfma_f32_16x16x32_bf16 v[104:107], v[170:173], v[202:205], v[104:107]
	v_mfma_f32_16x16x32_bf16 v[92:95], v[162:165], v[210:213], v[92:95]
	v_mfma_f32_16x16x32_bf16 v[88:91], v[170:173], v[210:213], v[88:91]
	v_mfma_f32_16x16x32_bf16 v[76:79], v[162:165], v[218:221], v[76:79]
	v_mfma_f32_16x16x32_bf16 v[72:75], v[170:173], v[218:221], v[72:75]
	v_mfma_f32_16x16x32_bf16 v[116:119], v[174:177], v[190:193], v[116:119]
	v_mfma_f32_16x16x32_bf16 v[112:115], v[182:185], v[190:193], v[112:115]
	v_mfma_f32_16x16x32_bf16 v[100:103], v[174:177], v[198:201], v[100:103]
	v_mfma_f32_16x16x32_bf16 v[96:99], v[182:185], v[198:201], v[96:99]
	v_mfma_f32_16x16x32_bf16 v[84:87], v[174:177], v[206:209], v[84:87]
	v_mfma_f32_16x16x32_bf16 v[80:83], v[182:185], v[206:209], v[80:83]
	v_mfma_f32_16x16x32_bf16 v[68:71], v[174:177], v[214:217], v[68:71]
	v_mfma_f32_16x16x32_bf16 v[64:67], v[182:185], v[214:217], v[64:67]
	v_mfma_f32_16x16x32_bf16 v[116:119], v[178:181], v[194:197], v[116:119]
	v_mfma_f32_16x16x32_bf16 v[112:115], v[186:189], v[194:197], v[112:115]
	v_mfma_f32_16x16x32_bf16 v[100:103], v[178:181], v[202:205], v[100:103]
	v_mfma_f32_16x16x32_bf16 v[96:99], v[186:189], v[202:205], v[96:99]
	v_mfma_f32_16x16x32_bf16 v[84:87], v[178:181], v[210:213], v[84:87]
	v_mfma_f32_16x16x32_bf16 v[80:83], v[186:189], v[210:213], v[80:83]
	v_mfma_f32_16x16x32_bf16 v[68:71], v[178:181], v[218:221], v[68:71]
	v_mfma_f32_16x16x32_bf16 v[64:67], v[186:189], v[218:221], v[64:67]
	s_setprio 0
	s_barrier
	s_add_i32 s59, s52, s41
	v_lshl_add_u64 v[222:223], s[30:31], 0, v[130:131]
	s_mov_b32 m0, s59
	ds_read_b128 v[190:193], v158 offset:16384
	ds_read_b128 v[194:197], v158 offset:17408
	ds_read_b128 v[198:201], v158 offset:18432
	ds_read_b128 v[202:205], v158 offset:19456
	ds_read_b128 v[206:209], v158 offset:20480
	ds_read_b128 v[210:213], v158 offset:21504
	ds_read_b128 v[214:217], v158 offset:22528
	ds_read_b128 v[218:221], v158 offset:23552
	global_load_lds_dwordx4 v[222:223], off
	s_add_i32 m0, s59, 0x2000
	s_add_u32 s60, s30, 0x40000
	v_lshl_add_u64 v[224:225], s[30:31], 0, v[134:135]
	s_addc_u32 s61, s31, 0
	s_add_i32 s59, s53, s41
	global_load_lds_dwordx4 v[224:225], off
	v_lshl_add_u64 v[226:227], s[60:61], 0, v[130:131]
	s_mov_b32 m0, s59
	v_lshl_add_u64 v[228:229], s[34:35], 0, v[132:133]
	global_load_lds_dwordx4 v[226:227], off
	v_lshl_add_u64 v[226:227], s[60:61], 0, v[134:135]
	s_add_i32 m0, s59, 0x2000
	s_nop 0
	global_load_lds_dwordx4 v[226:227], off
	v_lshl_add_u64 v[226:227], s[34:35], 0, v[128:129]
	s_mov_b32 m0, s27
	s_nop 0
	global_load_lds_dwordx4 v[226:227], off
	s_mov_b32 m0, s42
	s_nop 0
	global_load_lds_dwordx4 v[228:229], off
	s_waitcnt vmcnt(8)
	s_waitcnt lgkmcnt(0)
	s_barrier
; #define PG8_STAGE(bufoff, gbase, voff) do { _Pragma("unroll") for (int _i = 0; _i < 2; ++_i) \
;         __builtin_amdgcn_global_load_lds((const unsigned*)((const char*)(gbase) + (voff)[_i]), (LAS unsigned*)(lds + (bufoff) + ldsw + _i * 8192), 16, 0, 0); } while (0)
; #define PG8_LDA(dst, b, h) do { _Pragma("unroll") for (int m = 0; m < 4; ++m) _Pragma("unroll") for (int k = 0; k < 2; ++k) dst[m][k] = *(const LAS bf16x8*)(lds + PG8_SA(b, h) + aoff + m * 2048 + k * 1024); } while (0)
; #define PG8_LDB(dst, b, h) do { _Pragma("unroll") for (int n = 0; n < 2; ++n) _Pragma("unroll") for (int k = 0; k < 2; ++k) dst[n][k] = *(const LAS bf16x8*)(lds + PG8_SB(b, h) + boff + n * 2048 + k * 1024); } while (0)
; #define PG8_MMA(ai, bj, At, Bt) do { __builtin_amdgcn_s_setprio(1); _Pragma("unroll") for (int m = 0; m < 4; ++m) _Pragma("unroll") for (int n = 0; n < 2; ++n) _Pragma("unroll") for (int k = 0; k < 2; ++k) \
;         acc[ai][bj][m][n] = __builtin_amdgcn_mfma_f32_16x16x32_bf16(Bt[n][k], At[m][k], acc[ai][bj][m][n], 0, 0, 0); __builtin_amdgcn_s_setprio(0); } while (0)
; #define PG8_WAIT_V(n) asm volatile("s_waitcnt vmcnt(" #n ")" ::: "memory")
; #define PG8_WAIT_L(n) asm volatile("s_waitcnt lgkmcnt(" #n ")" ::: "memory")
; #define PG8_BAR __builtin_amdgcn_s_barrier()
; #define PG8_SCHED __builtin_amdgcn_sched_barrier(0)
; template <class Epi>
; __device__ __forceinline__ void gemm_phase(LAS unsigned char* lds, const int tid, const Gemm g, const StaticOrder& S, const Epi& E) {
;     ...
;             PG8_WAIT_V(8); PG8_WAIT_L(0); PG8_BAR; PG8_MMA(1, 0, At, B0); PG8_MMA(1, 1, At, B1); PG8_BAR; PG8_SCHED;
;             PG8_LDB(B0, 1, 0); PG8_LDB(B1, 1, 1); PG8_SCHED; PG8_LDA(At, 1, 0); PG8_STAGE(PG8_SA(0, 1), a2 + hstepA, voffA);
;             PG8_WAIT_V(8); PG8_WAIT_L(0); PG8_BAR; PG8_MMA(0, 0, At, B0); PG8_MMA(0, 1, At, B1); PG8_BAR; PG8_SCHED;
	s_setprio 1
	v_mfma_f32_16x16x32_bf16 v[60:63], v[152:155], v[190:193], v[60:63]
	v_mfma_f32_16x16x32_bf16 v[56:59], v[166:169], v[190:193], v[56:59]
	v_mfma_f32_16x16x32_bf16 v[44:47], v[152:155], v[198:201], v[44:47]
	v_mfma_f32_16x16x32_bf16 v[40:43], v[166:169], v[198:201], v[40:43]
	v_mfma_f32_16x16x32_bf16 v[28:31], v[152:155], v[206:209], v[28:31]
	v_mfma_f32_16x16x32_bf16 v[24:27], v[166:169], v[206:209], v[24:27]
	v_mfma_f32_16x16x32_bf16 v[12:15], v[152:155], v[214:217], v[12:15]
	v_mfma_f32_16x16x32_bf16 v[8:11], v[166:169], v[214:217], v[8:11]
	v_mfma_f32_16x16x32_bf16 v[60:63], v[162:165], v[194:197], v[60:63]
	v_mfma_f32_16x16x32_bf16 v[56:59], v[170:173], v[194:197], v[56:59]
	v_mfma_f32_16x16x32_bf16 v[44:47], v[162:165], v[202:205], v[44:47]
	v_mfma_f32_16x16x32_bf16 v[40:43], v[170:173], v[202:205], v[40:43]
	v_mfma_f32_16x16x32_bf16 v[28:31], v[162:165], v[210:213], v[28:31]
	v_mfma_f32_16x16x32_bf16 v[24:27], v[170:173], v[210:213], v[24:27]
	v_mfma_f32_16x16x32_bf16 v[12:15], v[162:165], v[218:221], v[12:15]
	v_mfma_f32_16x16x32_bf16 v[8:11], v[170:173], v[218:221], v[8:11]
	v_mfma_f32_16x16x32_bf16 v[52:55], v[174:177], v[190:193], v[52:55]
	v_mfma_f32_16x16x32_bf16 v[48:51], v[182:185], v[190:193], v[48:51]
	v_mfma_f32_16x16x32_bf16 v[36:39], v[174:177], v[198:201], v[36:39]
	v_mfma_f32_16x16x32_bf16 v[32:35], v[182:185], v[198:201], v[32:35]
	v_mfma_f32_16x16x32_bf16 v[20:23], v[174:177], v[206:209], v[20:23]
	v_mfma_f32_16x16x32_bf16 v[16:19], v[182:185], v[206:209], v[16:19]
	v_mfma_f32_16x16x32_bf16 v[4:7], v[174:177], v[214:217], v[4:7]
	v_mfma_f32_16x16x32_bf16 v[0:3], v[182:185], v[214:217], v[0:3]
	v_mfma_f32_16x16x32_bf16 v[52:55], v[178:181], v[194:197], v[52:55]
	v_mfma_f32_16x16x32_bf16 v[48:51], v[186:189], v[194:197], v[48:51]
	v_mfma_f32_16x16x32_bf16 v[36:39], v[178:181], v[202:205], v[36:39]
	v_mfma_f32_16x16x32_bf16 v[32:35], v[186:189], v[202:205], v[32:35]
	v_mfma_f32_16x16x32_bf16 v[20:23], v[178:181], v[210:213], v[20:23]
	v_mfma_f32_16x16x32_bf16 v[16:19], v[186:189], v[210:213], v[16:19]
	v_mfma_f32_16x16x32_bf16 v[4:7], v[178:181], v[218:221], v[4:7]
	v_mfma_f32_16x16x32_bf16 v[0:3], v[186:189], v[218:221], v[0:3]
	s_setprio 0
	s_barrier
	s_add_i32 s59, 0, 0x18000
	v_add_u32_e32 v161, s59, v157
	s_add_i32 s60, 0, 0x1c000
	ds_read_b128 v[152:155], v161
	ds_read_b128 v[162:165], v161 offset:1024
	ds_read_b128 v[166:169], v161 offset:2048
	ds_read_b128 v[170:173], v161 offset:3072
	v_add_u32_e32 v161, s60, v157
	ds_read_b128 v[174:177], v161
	ds_read_b128 v[178:181], v161 offset:1024
	ds_read_b128 v[182:185], v161 offset:2048
	ds_read_b128 v[186:189], v161 offset:3072
	s_add_u32 s34, s34, 0x40000
	s_addc_u32 s35, s35, 0
	s_mov_b32 m0, s43
	v_lshl_add_u64 v[230:231], s[34:35], 0, v[128:129]
	ds_read_b128 v[190:193], v158 offset:32768
	ds_read_b128 v[194:197], v158 offset:33792
	ds_read_b128 v[198:201], v158 offset:34816
	ds_read_b128 v[202:205], v158 offset:35840
	ds_read_b128 v[206:209], v158 offset:36864
	ds_read_b128 v[210:213], v158 offset:37888
	ds_read_b128 v[214:217], v158 offset:38912
	ds_read_b128 v[218:221], v158 offset:39936
	global_load_lds_dwordx4 v[230:231], off
	v_lshl_add_u64 v[230:231], s[34:35], 0, v[132:133]
	s_mov_b32 m0, s44
	s_nop 0
	global_load_lds_dwordx4 v[230:231], off
	s_waitcnt vmcnt(8)
	s_waitcnt lgkmcnt(0)
	s_barrier
	s_setprio 1
	v_mfma_f32_16x16x32_bf16 v[124:127], v[152:155], v[190:193], v[124:127]
	v_mfma_f32_16x16x32_bf16 v[120:123], v[166:169], v[190:193], v[120:123]
	v_mfma_f32_16x16x32_bf16 v[108:111], v[152:155], v[198:201], v[108:111]
	v_mfma_f32_16x16x32_bf16 v[104:107], v[166:169], v[198:201], v[104:107]
	v_mfma_f32_16x16x32_bf16 v[92:95], v[152:155], v[206:209], v[92:95]
	v_mfma_f32_16x16x32_bf16 v[88:91], v[166:169], v[206:209], v[88:91]
	v_mfma_f32_16x16x32_bf16 v[76:79], v[152:155], v[214:217], v[76:79]
	v_mfma_f32_16x16x32_bf16 v[72:75], v[166:169], v[214:217], v[72:75]
	v_mfma_f32_16x16x32_bf16 v[124:127], v[162:165], v[194:197], v[124:127]
	v_mfma_f32_16x16x32_bf16 v[120:123], v[170:173], v[194:197], v[120:123]
	v_mfma_f32_16x16x32_bf16 v[108:111], v[162:165], v[202:205], v[108:111]
	v_mfma_f32_16x16x32_bf16 v[104:107], v[170:173], v[202:205], v[104:107]
	v_mfma_f32_16x16x32_bf16 v[92:95], v[162:165], v[210:213], v[92:95]
	v_mfma_f32_16x16x32_bf16 v[88:91], v[170:173], v[210:213], v[88:91]
	v_mfma_f32_16x16x32_bf16 v[76:79], v[162:165], v[218:221], v[76:79]
	v_mfma_f32_16x16x32_bf16 v[72:75], v[170:173], v[218:221], v[72:75]
	v_mfma_f32_16x16x32_bf16 v[116:119], v[174:177], v[190:193], v[116:119]
	v_mfma_f32_16x16x32_bf16 v[112:115], v[182:185], v[190:193], v[112:115]
	v_mfma_f32_16x16x32_bf16 v[100:103], v[174:177], v[198:201], v[100:103]
	v_mfma_f32_16x16x32_bf16 v[96:99], v[182:185], v[198:201], v[96:99]
	v_mfma_f32_16x16x32_bf16 v[84:87], v[174:177], v[206:209], v[84:87]
	v_mfma_f32_16x16x32_bf16 v[80:83], v[182:185], v[206:209], v[80:83]
	v_mfma_f32_16x16x32_bf16 v[68:71], v[174:177], v[214:217], v[68:71]
	v_mfma_f32_16x16x32_bf16 v[64:67], v[182:185], v[214:217], v[64:67]
	v_mfma_f32_16x16x32_bf16 v[116:119], v[178:181], v[194:197], v[116:119]
	v_mfma_f32_16x16x32_bf16 v[112:115], v[186:189], v[194:197], v[112:115]
	v_mfma_f32_16x16x32_bf16 v[100:103], v[178:181], v[202:205], v[100:103]
	v_mfma_f32_16x16x32_bf16 v[96:99], v[186:189], v[202:205], v[96:99]
	v_mfma_f32_16x16x32_bf16 v[84:87], v[178:181], v[210:213], v[84:87]
	v_mfma_f32_16x16x32_bf16 v[80:83], v[186:189], v[210:213], v[80:83]
	v_mfma_f32_16x16x32_bf16 v[68:71], v[178:181], v[218:221], v[68:71]
	v_mfma_f32_16x16x32_bf16 v[64:67], v[186:189], v[218:221], v[64:67]
	s_setprio 0
	s_barrier
; #define PG8_STAGE(bufoff, gbase, voff) do { _Pragma("unroll") for (int _i = 0; _i < 2; ++_i) \
;         __builtin_amdgcn_global_load_lds((const unsigned*)((const char*)(gbase) + (voff)[_i]), (LAS unsigned*)(lds + (bufoff) + ldsw + _i * 8192), 16, 0, 0); } while (0)
; #define PG8_LDA(dst, b, h) do { _Pragma("unroll") for (int m = 0; m < 4; ++m) _Pragma("unroll") for (int k = 0; k < 2; ++k) dst[m][k] = *(const LAS bf16x8*)(lds + PG8_SA(b, h) + aoff + m * 2048 + k * 1024); } while (0)
; #define PG8_MMA(ai, bj, At, Bt) do { __builtin_amdgcn_s_setprio(1); _Pragma("unroll") for (int m = 0; m < 4; ++m) _Pragma("unroll") for (int n = 0; n < 2; ++n) _Pragma("unroll") for (int k = 0; k < 2; ++k) \
;         acc[ai][bj][m][n] = __builtin_amdgcn_mfma_f32_16x16x32_bf16(Bt[n][k], At[m][k], acc[ai][bj][m][n], 0, 0, 0); __builtin_amdgcn_s_setprio(0); } while (0)
; #define PG8_WAIT_V(n) asm volatile("s_waitcnt vmcnt(" #n ")" ::: "memory")
; #define PG8_WAIT_L(n) asm volatile("s_waitcnt lgkmcnt(" #n ")" ::: "memory")
; #define PG8_BAR __builtin_amdgcn_s_barrier()
; #define PG8_SCHED __builtin_amdgcn_sched_barrier(0)
; template <class Epi>
; __device__ __forceinline__ void gemm_phase(LAS unsigned char* lds, const int tid, const Gemm g, const StaticOrder& S, const Epi& E) {
;     ...
;         for (int t = 0; t < nt; t += 2) {
;             const bool last = (t == nt - 2);
;             const char* a1 = cA + (size_t)(t + 1) * kstep;
;             const char* a2 = last ? nA : cA + (size_t)(t + 2) * kstep; const char* b2 = last ? nB : cB + (size_t)(t + 2) * kstep;
;             const char* a3 = a2 + kstep; const char* b3 = b2 + kstep;
;             if constexpr (Epi::SS_LDS) { if (last) {
;     ...
;             PG8_LDA(At, 1, 1); PG8_STAGE(PG8_SB(1, 0), b3, voffB); PG8_STAGE(PG8_SB(1, 1), b3 + hstepB, voffB); PG8_STAGE(PG8_SA(1, 0), a3, voffA);
;             PG8_WAIT_V(8); PG8_WAIT_L(0); PG8_BAR; PG8_MMA(1, 0, At, B0); PG8_MMA(1, 1, At, B1); PG8_BAR; PG8_SCHED;
	s_add_i32 s34, s59, s41
	v_lshl_add_u64 v[222:223], v[222:223], 0, s[10:11]
	s_mov_b32 m0, s34
	ds_read_b128 v[190:193], v158 offset:49152
	ds_read_b128 v[194:197], v158 offset:50176
	ds_read_b128 v[198:201], v158 offset:51200
	ds_read_b128 v[202:205], v158 offset:52224
	ds_read_b128 v[206:209], v158 offset:53248
	ds_read_b128 v[210:213], v158 offset:54272
	ds_read_b128 v[214:217], v158 offset:55296
	ds_read_b128 v[218:221], v158 offset:56320
	global_load_lds_dwordx4 v[222:223], off
	s_add_i32 m0, s34, 0x2000
	s_add_u32 s30, s30, 0x40080
	v_lshl_add_u64 v[222:223], v[224:225], 0, s[10:11]
	s_addc_u32 s31, s31, 0
	s_add_i32 s34, s60, s41
	global_load_lds_dwordx4 v[222:223], off
	v_lshl_add_u64 v[222:223], s[30:31], 0, v[130:131]
	s_mov_b32 m0, s34
	s_nop 0
	global_load_lds_dwordx4 v[222:223], off
	v_lshl_add_u64 v[222:223], s[30:31], 0, v[134:135]
	s_add_i32 m0, s34, 0x2000
	s_nop 0
	global_load_lds_dwordx4 v[222:223], off
	v_lshl_add_u64 v[222:223], v[226:227], 0, s[10:11]
	s_mov_b32 m0, s47
	s_nop 0
	global_load_lds_dwordx4 v[222:223], off
	v_lshl_add_u64 v[222:223], v[228:229], 0, s[10:11]
	s_mov_b32 m0, s48
	s_nop 0
	global_load_lds_dwordx4 v[222:223], off
	s_add_u32 s5, s5, 0x100
	s_addc_u32 s57, s57, 0
	s_add_u32 s28, s28, 0x100
	s_addc_u32 s29, s29, 0
	s_cmp_eq_u32 s49, s58
	s_cselect_b64 s[30:31], -1, 0
	s_waitcnt vmcnt(8)
	s_waitcnt lgkmcnt(0)
	s_barrier
	s_setprio 1
	v_mfma_f32_16x16x32_bf16 v[60:63], v[152:155], v[190:193], v[60:63]
	v_mfma_f32_16x16x32_bf16 v[56:59], v[166:169], v[190:193], v[56:59]
	v_mfma_f32_16x16x32_bf16 v[44:47], v[152:155], v[198:201], v[44:47]
	v_mfma_f32_16x16x32_bf16 v[40:43], v[166:169], v[198:201], v[40:43]
	v_mfma_f32_16x16x32_bf16 v[28:31], v[152:155], v[206:209], v[28:31]
	v_mfma_f32_16x16x32_bf16 v[24:27], v[166:169], v[206:209], v[24:27]
	v_mfma_f32_16x16x32_bf16 v[12:15], v[152:155], v[214:217], v[12:15]
	v_mfma_f32_16x16x32_bf16 v[8:11], v[166:169], v[214:217], v[8:11]
	v_mfma_f32_16x16x32_bf16 v[60:63], v[162:165], v[194:197], v[60:63]
	v_mfma_f32_16x16x32_bf16 v[56:59], v[170:173], v[194:197], v[56:59]
	v_mfma_f32_16x16x32_bf16 v[44:47], v[162:165], v[202:205], v[44:47]
	v_mfma_f32_16x16x32_bf16 v[40:43], v[170:173], v[202:205], v[40:43]
	v_mfma_f32_16x16x32_bf16 v[28:31], v[162:165], v[210:213], v[28:31]
	v_mfma_f32_16x16x32_bf16 v[24:27], v[170:173], v[210:213], v[24:27]
	v_mfma_f32_16x16x32_bf16 v[12:15], v[162:165], v[218:221], v[12:15]
	v_mfma_f32_16x16x32_bf16 v[8:11], v[170:173], v[218:221], v[8:11]
	v_mfma_f32_16x16x32_bf16 v[52:55], v[174:177], v[190:193], v[52:55]
	v_mfma_f32_16x16x32_bf16 v[48:51], v[182:185], v[190:193], v[48:51]
	v_mfma_f32_16x16x32_bf16 v[36:39], v[174:177], v[198:201], v[36:39]
	v_mfma_f32_16x16x32_bf16 v[32:35], v[182:185], v[198:201], v[32:35]
	v_mfma_f32_16x16x32_bf16 v[20:23], v[174:177], v[206:209], v[20:23]
	v_mfma_f32_16x16x32_bf16 v[16:19], v[182:185], v[206:209], v[16:19]
	v_mfma_f32_16x16x32_bf16 v[4:7], v[174:177], v[214:217], v[4:7]
	v_mfma_f32_16x16x32_bf16 v[0:3], v[182:185], v[214:217], v[0:3]
	v_mfma_f32_16x16x32_bf16 v[52:55], v[178:181], v[194:197], v[52:55]
	v_mfma_f32_16x16x32_bf16 v[48:51], v[186:189], v[194:197], v[48:51]
	v_mfma_f32_16x16x32_bf16 v[36:39], v[178:181], v[202:205], v[36:39]
	v_mfma_f32_16x16x32_bf16 v[32:35], v[186:189], v[202:205], v[32:35]
	v_mfma_f32_16x16x32_bf16 v[20:23], v[178:181], v[210:213], v[20:23]
	v_mfma_f32_16x16x32_bf16 v[16:19], v[186:189], v[210:213], v[16:19]
	v_mfma_f32_16x16x32_bf16 v[4:7], v[178:181], v[218:221], v[4:7]
	v_mfma_f32_16x16x32_bf16 v[0:3], v[186:189], v[218:221], v[0:3]
	s_setprio 0
	s_barrier
	s_cmp_ge_i32 s58, s46
	s_cbranch_scc1 .LBB0_1315
	s_cmp_lg_u32 s49, s58
	s_cbranch_scc1 .LBB0_1312
	s_branch .Lrs_6

; #define LAS __attribute__((address_space(3)))
; template <class Epi>
; __device__ __forceinline__ void gemm_phase(LAS unsigned char* lds, const int tid, const Gemm g, const StaticOrder& S, const Epi& E) {
;     ...
;             if constexpr (Epi::SS_LDS) { if (last) {
;                 const char* sp = (const char*)E.ss + (size_t)cur.pm * (256 * 64) + (size_t)tid * 16;
;                 __builtin_amdgcn_global_load_lds((const unsigned*)sp, (LAS unsigned*)(lds + RS_OFF + ldsw), 16, 0, 0);
;                 __builtin_amdgcn_global_load_lds((const unsigned*)(sp + 8192), (LAS unsigned*)(lds + RS_OFF + 8192 + ldsw), 16, 0, 0); } }
.Lrs_6:
	s_add_i32 m0, s27, 0x20800
	s_nop 0
	global_load_lds_dwordx4 v[148:149], off
	s_add_i32 m0, s27, 0x22800
	s_nop 0
	global_load_lds_dwordx4 v[150:151], off
	s_branch .LBB0_1312

; #define LAS __attribute__((address_space(3)))
; #define PG8_STAGE(bufoff, gbase, voff) do { _Pragma("unroll") for (int _i = 0; _i < 2; ++_i) \
;         __builtin_amdgcn_global_load_lds((const unsigned*)((const char*)(gbase) + (voff)[_i]), (LAS unsigned*)(lds + (bufoff) + ldsw + _i * 8192), 16, 0, 0); } while (0)
; #define PG8_LDA(dst, b, h) do { _Pragma("unroll") for (int m = 0; m < 4; ++m) _Pragma("unroll") for (int k = 0; k < 2; ++k) dst[m][k] = *(const LAS bf16x8*)(lds + PG8_SA(b, h) + aoff + m * 2048 + k * 1024); } while (0)
; #define PG8_LDB(dst, b, h) do { _Pragma("unroll") for (int n = 0; n < 2; ++n) _Pragma("unroll") for (int k = 0; k < 2; ++k) dst[n][k] = *(const LAS bf16x8*)(lds + PG8_SB(b, h) + boff + n * 2048 + k * 1024); } while (0)
; #define PG8_WAIT_V(n) asm volatile("s_waitcnt vmcnt(" #n ")" ::: "memory")
; #define PG8_WAIT_L(n) asm volatile("s_waitcnt lgkmcnt(" #n ")" ::: "memory")
; #define PG8_BAR __builtin_amdgcn_s_barrier()
; template <class Epi>
; __device__ __forceinline__ void gemm_phase(LAS unsigned char* lds, const int tid, const Gemm g, const StaticOrder& S, const Epi& E) {
;     ...
;             const bool last = (t == nt - 2);
;             const char* a1 = cA + (size_t)(t + 1) * kstep;
;             const char* a2 = last ? nA : cA + (size_t)(t + 2) * kstep; const char* b2 = last ? nB : cB + (size_t)(t + 2) * kstep;
;             const char* a3 = a2 + kstep; const char* b3 = b2 + kstep;
;             if constexpr (Epi::SS_LDS) { if (last) {
;                 const char* sp = (const char*)E.ss + (size_t)cur.pm * (256 * 64) + (size_t)tid * 16;
;                 __builtin_amdgcn_global_load_lds((const unsigned*)sp, (LAS unsigned*)(lds + RS_OFF + ldsw), 16, 0, 0);
;                 __builtin_amdgcn_global_load_lds((const unsigned*)(sp + 8192), (LAS unsigned*)(lds + RS_OFF + 8192 + ldsw), 16, 0, 0); } }
;     ...
;             PG8_LDB(B0, 0, 0); PG8_LDB(B1, 0, 1); PG8_SCHED; PG8_LDA(At, 0, 0); PG8_STAGE(PG8_SA(1, 1), a1 + hstepA, voffA);
;             PG8_WAIT_V(8); PG8_WAIT_L(0); PG8_BAR; PG8_MMA(0, 0, At, B0); PG8_MMA(0, 1, At, B1); PG8_BAR; PG8_SCHED;
;             PG8_LDA(At, 0, 1); PG8_STAGE(PG8_SB(0, 0), b2, voffB); PG8_STAGE(PG8_SB(0, 1), b2 + hstepB, voffB); PG8_STAGE(PG8_SA(0, 0), a2, voffA);
;             PG8_WAIT_V(8); PG8_WAIT_L(0); PG8_BAR; PG8_MMA(1, 0, At, B0); PG8_MMA(1, 1, At, B1); PG8_BAR; PG8_SCHED;
.LBB0_2036:
	v_add_u32_e32 v144, s50, v213
	v_add_u32_e32 v160, s51, v213
	ds_read_b128 v[132:135], v144
	ds_read_b128 v[136:139], v144 offset:1024
	ds_read_b128 v[140:143], v144 offset:2048
	ds_read_b128 v[144:147], v144 offset:3072
	ds_read_b128 v[148:151], v160
	ds_read_b128 v[152:155], v160 offset:1024
	ds_read_b128 v[156:159], v160 offset:2048
	ds_read_b128 v[160:163], v160 offset:3072
	s_add_i32 s55, s55, 2
	s_add_u32 s34, s28, 0xfffc0080
	s_addc_u32 s35, s29, -1
	s_and_b64 s[30:31], s[30:31], exec
	s_cselect_b32 s35, s19, s35
	s_cselect_b32 s34, s21, s34
	s_cselect_b32 s31, s52, s54
	s_cselect_b32 s30, s53, s27
	v_lshl_add_u64 v[210:211], s[28:29], 0, v[196:197]
	s_add_i32 m0, s40, 0xc000
	ds_read_b128 v[164:167], v215
	ds_read_b128 v[168:171], v215 offset:1024
	ds_read_b128 v[172:175], v215 offset:2048
	ds_read_b128 v[176:179], v215 offset:3072
	ds_read_b128 v[180:183], v215 offset:4096
	ds_read_b128 v[202:205], v215 offset:5120
	ds_read_b128 v[206:209], v215 offset:6144
	ds_read_b128 v[218:221], v215 offset:7168
	global_load_lds_dwordx4 v[210:211], off
	v_lshl_add_u64 v[210:211], s[28:29], 0, v[194:195]
	s_add_i32 m0, s40, 0xe000
	s_nop 0
	global_load_lds_dwordx4 v[210:211], off
	s_waitcnt vmcnt(8)
	s_waitcnt lgkmcnt(0)
	s_barrier
	s_setprio 1
	v_mfma_f32_16x16x32_bf16 v[124:127], v[132:135], v[164:167], v[124:127]
	v_mfma_f32_16x16x32_bf16 v[120:123], v[140:143], v[164:167], v[120:123]
	v_mfma_f32_16x16x32_bf16 v[108:111], v[132:135], v[172:175], v[108:111]
	v_mfma_f32_16x16x32_bf16 v[104:107], v[140:143], v[172:175], v[104:107]
	v_mfma_f32_16x16x32_bf16 v[92:95], v[132:135], v[180:183], v[92:95]
	v_mfma_f32_16x16x32_bf16 v[88:91], v[140:143], v[180:183], v[88:91]
	v_mfma_f32_16x16x32_bf16 v[76:79], v[132:135], v[206:209], v[76:79]
	v_mfma_f32_16x16x32_bf16 v[72:75], v[140:143], v[206:209], v[72:75]
	v_mfma_f32_16x16x32_bf16 v[124:127], v[136:139], v[168:171], v[124:127]
	v_mfma_f32_16x16x32_bf16 v[120:123], v[144:147], v[168:171], v[120:123]
	v_mfma_f32_16x16x32_bf16 v[108:111], v[136:139], v[176:179], v[108:111]
	v_mfma_f32_16x16x32_bf16 v[104:107], v[144:147], v[176:179], v[104:107]
	v_mfma_f32_16x16x32_bf16 v[92:95], v[136:139], v[202:205], v[92:95]
	v_mfma_f32_16x16x32_bf16 v[88:91], v[144:147], v[202:205], v[88:91]
	v_mfma_f32_16x16x32_bf16 v[76:79], v[136:139], v[218:221], v[76:79]
	v_mfma_f32_16x16x32_bf16 v[72:75], v[144:147], v[218:221], v[72:75]
	v_mfma_f32_16x16x32_bf16 v[116:119], v[148:151], v[164:167], v[116:119]
	v_mfma_f32_16x16x32_bf16 v[112:115], v[156:159], v[164:167], v[112:115]
	v_mfma_f32_16x16x32_bf16 v[100:103], v[148:151], v[172:175], v[100:103]
	v_mfma_f32_16x16x32_bf16 v[96:99], v[156:159], v[172:175], v[96:99]
	v_mfma_f32_16x16x32_bf16 v[84:87], v[148:151], v[180:183], v[84:87]
	v_mfma_f32_16x16x32_bf16 v[80:83], v[156:159], v[180:183], v[80:83]
	v_mfma_f32_16x16x32_bf16 v[68:71], v[148:151], v[206:209], v[68:71]
	v_mfma_f32_16x16x32_bf16 v[64:67], v[156:159], v[206:209], v[64:67]
	v_mfma_f32_16x16x32_bf16 v[116:119], v[152:155], v[168:171], v[116:119]
	v_mfma_f32_16x16x32_bf16 v[112:115], v[160:163], v[168:171], v[112:115]
	v_mfma_f32_16x16x32_bf16 v[100:103], v[152:155], v[176:179], v[100:103]
	v_mfma_f32_16x16x32_bf16 v[96:99], v[160:163], v[176:179], v[96:99]
	v_mfma_f32_16x16x32_bf16 v[84:87], v[152:155], v[202:205], v[84:87]
	v_mfma_f32_16x16x32_bf16 v[80:83], v[160:163], v[202:205], v[80:83]
	v_mfma_f32_16x16x32_bf16 v[68:71], v[152:155], v[218:221], v[68:71]
	v_mfma_f32_16x16x32_bf16 v[64:67], v[160:163], v[218:221], v[64:67]
	s_setprio 0
	s_barrier
	s_add_i32 s56, s50, s39
	v_lshl_add_u64 v[210:211], s[30:31], 0, v[186:187]
	s_mov_b32 m0, s56
	ds_read_b128 v[164:167], v215 offset:16384
	ds_read_b128 v[168:171], v215 offset:17408
	ds_read_b128 v[172:175], v215 offset:18432
	ds_read_b128 v[176:179], v215 offset:19456
	ds_read_b128 v[180:183], v215 offset:20480
	ds_read_b128 v[202:205], v215 offset:21504
	ds_read_b128 v[206:209], v215 offset:22528
	ds_read_b128 v[218:221], v215 offset:23552
	global_load_lds_dwordx4 v[210:211], off
	s_add_i32 m0, s56, 0x2000
	s_add_u32 s56, s30, 0x40000
	v_lshl_add_u64 v[222:223], s[30:31], 0, v[190:191]
	s_addc_u32 s57, s31, 0
	s_add_i32 s58, s51, s39
	global_load_lds_dwordx4 v[222:223], off
	v_lshl_add_u64 v[224:225], s[56:57], 0, v[186:187]
	s_mov_b32 m0, s58
	v_lshl_add_u64 v[226:227], s[34:35], 0, v[188:189]
	global_load_lds_dwordx4 v[224:225], off
	v_lshl_add_u64 v[224:225], s[56:57], 0, v[190:191]
	s_add_i32 m0, s58, 0x2000
	s_nop 0
	global_load_lds_dwordx4 v[224:225], off
	v_lshl_add_u64 v[224:225], s[34:35], 0, v[184:185]
	s_mov_b32 m0, s40
	s_nop 0
	global_load_lds_dwordx4 v[224:225], off
	s_mov_b32 m0, s41
	s_nop 0
	global_load_lds_dwordx4 v[226:227], off
	s_waitcnt vmcnt(8)
	s_waitcnt lgkmcnt(0)
	s_barrier
; #define PG8_STAGE(bufoff, gbase, voff) do { _Pragma("unroll") for (int _i = 0; _i < 2; ++_i) \
;         __builtin_amdgcn_global_load_lds((const unsigned*)((const char*)(gbase) + (voff)[_i]), (LAS unsigned*)(lds + (bufoff) + ldsw + _i * 8192), 16, 0, 0); } while (0)
; #define PG8_LDA(dst, b, h) do { _Pragma("unroll") for (int m = 0; m < 4; ++m) _Pragma("unroll") for (int k = 0; k < 2; ++k) dst[m][k] = *(const LAS bf16x8*)(lds + PG8_SA(b, h) + aoff + m * 2048 + k * 1024); } while (0)
; #define PG8_LDB(dst, b, h) do { _Pragma("unroll") for (int n = 0; n < 2; ++n) _Pragma("unroll") for (int k = 0; k < 2; ++k) dst[n][k] = *(const LAS bf16x8*)(lds + PG8_SB(b, h) + boff + n * 2048 + k * 1024); } while (0)
; #define PG8_MMA(ai, bj, At, Bt) do { __builtin_amdgcn_s_setprio(1); _Pragma("unroll") for (int m = 0; m < 4; ++m) _Pragma("unroll") for (int n = 0; n < 2; ++n) _Pragma("unroll") for (int k = 0; k < 2; ++k) \
;         acc[ai][bj][m][n] = __builtin_amdgcn_mfma_f32_16x16x32_bf16(Bt[n][k], At[m][k], acc[ai][bj][m][n], 0, 0, 0); __builtin_amdgcn_s_setprio(0); } while (0)
; #define PG8_WAIT_V(n) asm volatile("s_waitcnt vmcnt(" #n ")" ::: "memory")
; #define PG8_WAIT_L(n) asm volatile("s_waitcnt lgkmcnt(" #n ")" ::: "memory")
; #define PG8_BAR __builtin_amdgcn_s_barrier()
; #define PG8_SCHED __builtin_amdgcn_sched_barrier(0)
; template <class Epi>
; __device__ __forceinline__ void gemm_phase(LAS unsigned char* lds, const int tid, const Gemm g, const StaticOrder& S, const Epi& E) {
;     ...
;             PG8_WAIT_V(8); PG8_WAIT_L(0); PG8_BAR; PG8_MMA(1, 0, At, B0); PG8_MMA(1, 1, At, B1); PG8_BAR; PG8_SCHED;
;             PG8_LDB(B0, 1, 0); PG8_LDB(B1, 1, 1); PG8_SCHED; PG8_LDA(At, 1, 0); PG8_STAGE(PG8_SA(0, 1), a2 + hstepA, voffA);
;             PG8_WAIT_V(8); PG8_WAIT_L(0); PG8_BAR; PG8_MMA(0, 0, At, B0); PG8_MMA(0, 1, At, B1); PG8_BAR; PG8_SCHED;
	s_setprio 1
	v_mfma_f32_16x16x32_bf16 v[60:63], v[132:135], v[164:167], v[60:63]
	v_mfma_f32_16x16x32_bf16 v[56:59], v[140:143], v[164:167], v[56:59]
	v_mfma_f32_16x16x32_bf16 v[44:47], v[132:135], v[172:175], v[44:47]
	v_mfma_f32_16x16x32_bf16 v[40:43], v[140:143], v[172:175], v[40:43]
	v_mfma_f32_16x16x32_bf16 v[28:31], v[132:135], v[180:183], v[28:31]
	v_mfma_f32_16x16x32_bf16 v[24:27], v[140:143], v[180:183], v[24:27]
	v_mfma_f32_16x16x32_bf16 v[12:15], v[132:135], v[206:209], v[12:15]
	v_mfma_f32_16x16x32_bf16 v[8:11], v[140:143], v[206:209], v[8:11]
	v_mfma_f32_16x16x32_bf16 v[60:63], v[136:139], v[168:171], v[60:63]
	v_mfma_f32_16x16x32_bf16 v[56:59], v[144:147], v[168:171], v[56:59]
	v_mfma_f32_16x16x32_bf16 v[44:47], v[136:139], v[176:179], v[44:47]
	v_mfma_f32_16x16x32_bf16 v[40:43], v[144:147], v[176:179], v[40:43]
	v_mfma_f32_16x16x32_bf16 v[28:31], v[136:139], v[202:205], v[28:31]
	v_mfma_f32_16x16x32_bf16 v[24:27], v[144:147], v[202:205], v[24:27]
	v_mfma_f32_16x16x32_bf16 v[12:15], v[136:139], v[218:221], v[12:15]
	v_mfma_f32_16x16x32_bf16 v[8:11], v[144:147], v[218:221], v[8:11]
	v_mfma_f32_16x16x32_bf16 v[52:55], v[148:151], v[164:167], v[52:55]
	v_mfma_f32_16x16x32_bf16 v[48:51], v[156:159], v[164:167], v[48:51]
	v_mfma_f32_16x16x32_bf16 v[36:39], v[148:151], v[172:175], v[36:39]
	v_mfma_f32_16x16x32_bf16 v[32:35], v[156:159], v[172:175], v[32:35]
	v_mfma_f32_16x16x32_bf16 v[20:23], v[148:151], v[180:183], v[20:23]
	v_mfma_f32_16x16x32_bf16 v[16:19], v[156:159], v[180:183], v[16:19]
	v_mfma_f32_16x16x32_bf16 v[4:7], v[148:151], v[206:209], v[4:7]
	v_mfma_f32_16x16x32_bf16 v[0:3], v[156:159], v[206:209], v[0:3]
	v_mfma_f32_16x16x32_bf16 v[52:55], v[152:155], v[168:171], v[52:55]
	v_mfma_f32_16x16x32_bf16 v[48:51], v[160:163], v[168:171], v[48:51]
	v_mfma_f32_16x16x32_bf16 v[36:39], v[152:155], v[176:179], v[36:39]
	v_mfma_f32_16x16x32_bf16 v[32:35], v[160:163], v[176:179], v[32:35]
	v_mfma_f32_16x16x32_bf16 v[20:23], v[152:155], v[202:205], v[20:23]
	v_mfma_f32_16x16x32_bf16 v[16:19], v[160:163], v[202:205], v[16:19]
	v_mfma_f32_16x16x32_bf16 v[4:7], v[152:155], v[218:221], v[4:7]
	v_mfma_f32_16x16x32_bf16 v[0:3], v[160:163], v[218:221], v[0:3]
	s_setprio 0
	s_barrier
	s_add_i32 s56, 0, 0x18000
	s_add_i32 s57, 0, 0x1c000
	v_add_u32_e32 v144, s56, v213
	v_add_u32_e32 v160, s57, v213
	ds_read_b128 v[132:135], v144
	ds_read_b128 v[136:139], v144 offset:1024
	ds_read_b128 v[140:143], v144 offset:2048
	ds_read_b128 v[144:147], v144 offset:3072
	ds_read_b128 v[148:151], v160
	ds_read_b128 v[152:155], v160 offset:1024
	ds_read_b128 v[156:159], v160 offset:2048
	ds_read_b128 v[160:163], v160 offset:3072
	s_add_u32 s34, s34, 0x40000
	s_addc_u32 s35, s35, 0
	s_mov_b32 m0, s42
	v_lshl_add_u64 v[228:229], s[34:35], 0, v[184:185]
	ds_read_b128 v[164:167], v215 offset:32768
	ds_read_b128 v[168:171], v215 offset:33792
	ds_read_b128 v[172:175], v215 offset:34816
	ds_read_b128 v[176:179], v215 offset:35840
	ds_read_b128 v[180:183], v215 offset:36864
	ds_read_b128 v[202:205], v215 offset:37888
	ds_read_b128 v[206:209], v215 offset:38912
	ds_read_b128 v[218:221], v215 offset:39936
	global_load_lds_dwordx4 v[228:229], off
	v_lshl_add_u64 v[228:229], s[34:35], 0, v[188:189]
	s_mov_b32 m0, s43
	s_nop 0
	global_load_lds_dwordx4 v[228:229], off
	s_waitcnt vmcnt(8)
	s_waitcnt lgkmcnt(0)
	s_barrier
	s_setprio 1
	v_mfma_f32_16x16x32_bf16 v[124:127], v[132:135], v[164:167], v[124:127]
	v_mfma_f32_16x16x32_bf16 v[120:123], v[140:143], v[164:167], v[120:123]
	v_mfma_f32_16x16x32_bf16 v[108:111], v[132:135], v[172:175], v[108:111]
	v_mfma_f32_16x16x32_bf16 v[104:107], v[140:143], v[172:175], v[104:107]
	v_mfma_f32_16x16x32_bf16 v[92:95], v[132:135], v[180:183], v[92:95]
	v_mfma_f32_16x16x32_bf16 v[88:91], v[140:143], v[180:183], v[88:91]
	v_mfma_f32_16x16x32_bf16 v[76:79], v[132:135], v[206:209], v[76:79]
	v_mfma_f32_16x16x32_bf16 v[72:75], v[140:143], v[206:209], v[72:75]
	v_mfma_f32_16x16x32_bf16 v[124:127], v[136:139], v[168:171], v[124:127]
	v_mfma_f32_16x16x32_bf16 v[120:123], v[144:147], v[168:171], v[120:123]
	v_mfma_f32_16x16x32_bf16 v[108:111], v[136:139], v[176:179], v[108:111]
	v_mfma_f32_16x16x32_bf16 v[104:107], v[144:147], v[176:179], v[104:107]
	v_mfma_f32_16x16x32_bf16 v[92:95], v[136:139], v[202:205], v[92:95]
	v_mfma_f32_16x16x32_bf16 v[88:91], v[144:147], v[202:205], v[88:91]
	v_mfma_f32_16x16x32_bf16 v[76:79], v[136:139], v[218:221], v[76:79]
	v_mfma_f32_16x16x32_bf16 v[72:75], v[144:147], v[218:221], v[72:75]
	v_mfma_f32_16x16x32_bf16 v[116:119], v[148:151], v[164:167], v[116:119]
	v_mfma_f32_16x16x32_bf16 v[112:115], v[156:159], v[164:167], v[112:115]
	v_mfma_f32_16x16x32_bf16 v[100:103], v[148:151], v[172:175], v[100:103]
	v_mfma_f32_16x16x32_bf16 v[96:99], v[156:159], v[172:175], v[96:99]
	v_mfma_f32_16x16x32_bf16 v[84:87], v[148:151], v[180:183], v[84:87]
	v_mfma_f32_16x16x32_bf16 v[80:83], v[156:159], v[180:183], v[80:83]
	v_mfma_f32_16x16x32_bf16 v[68:71], v[148:151], v[206:209], v[68:71]
	v_mfma_f32_16x16x32_bf16 v[64:67], v[156:159], v[206:209], v[64:67]
	v_mfma_f32_16x16x32_bf16 v[116:119], v[152:155], v[168:171], v[116:119]
	v_mfma_f32_16x16x32_bf16 v[112:115], v[160:163], v[168:171], v[112:115]
	v_mfma_f32_16x16x32_bf16 v[100:103], v[152:155], v[176:179], v[100:103]
	v_mfma_f32_16x16x32_bf16 v[96:99], v[160:163], v[176:179], v[96:99]
	v_mfma_f32_16x16x32_bf16 v[84:87], v[152:155], v[202:205], v[84:87]
	v_mfma_f32_16x16x32_bf16 v[80:83], v[160:163], v[202:205], v[80:83]
	v_mfma_f32_16x16x32_bf16 v[68:71], v[152:155], v[218:221], v[68:71]
	v_mfma_f32_16x16x32_bf16 v[64:67], v[160:163], v[218:221], v[64:67]
	s_setprio 0
	s_barrier
; #define PG8_STAGE(bufoff, gbase, voff) do { _Pragma("unroll") for (int _i = 0; _i < 2; ++_i) \
;         __builtin_amdgcn_global_load_lds((const unsigned*)((const char*)(gbase) + (voff)[_i]), (LAS unsigned*)(lds + (bufoff) + ldsw + _i * 8192), 16, 0, 0); } while (0)
; #define PG8_LDA(dst, b, h) do { _Pragma("unroll") for (int m = 0; m < 4; ++m) _Pragma("unroll") for (int k = 0; k < 2; ++k) dst[m][k] = *(const LAS bf16x8*)(lds + PG8_SA(b, h) + aoff + m * 2048 + k * 1024); } while (0)
; #define PG8_MMA(ai, bj, At, Bt) do { __builtin_amdgcn_s_setprio(1); _Pragma("unroll") for (int m = 0; m < 4; ++m) _Pragma("unroll") for (int n = 0; n < 2; ++n) _Pragma("unroll") for (int k = 0; k < 2; ++k) \
;         acc[ai][bj][m][n] = __builtin_amdgcn_mfma_f32_16x16x32_bf16(Bt[n][k], At[m][k], acc[ai][bj][m][n], 0, 0, 0); __builtin_amdgcn_s_setprio(0); } while (0)
; #define PG8_WAIT_V(n) asm volatile("s_waitcnt vmcnt(" #n ")" ::: "memory")
; #define PG8_WAIT_L(n) asm volatile("s_waitcnt lgkmcnt(" #n ")" ::: "memory")
; #define PG8_BAR __builtin_amdgcn_s_barrier()
; #define PG8_SCHED __builtin_amdgcn_sched_barrier(0)
; template <class Epi>
; __device__ __forceinline__ void gemm_phase(LAS unsigned char* lds, const int tid, const Gemm g, const StaticOrder& S, const Epi& E) {
;     ...
;         for (int t = 0; t < nt; t += 2) {
;             const bool last = (t == nt - 2);
;             const char* a1 = cA + (size_t)(t + 1) * kstep;
;             const char* a2 = last ? nA : cA + (size_t)(t + 2) * kstep; const char* b2 = last ? nB : cB + (size_t)(t + 2) * kstep;
;             const char* a3 = a2 + kstep; const char* b3 = b2 + kstep;
;             if constexpr (Epi::SS_LDS) { if (last) {
;     ...
;             PG8_LDA(At, 1, 1); PG8_STAGE(PG8_SB(1, 0), b3, voffB); PG8_STAGE(PG8_SB(1, 1), b3 + hstepB, voffB); PG8_STAGE(PG8_SA(1, 0), a3, voffA);
;             PG8_WAIT_V(8); PG8_WAIT_L(0); PG8_BAR; PG8_MMA(1, 0, At, B0); PG8_MMA(1, 1, At, B1); PG8_BAR; PG8_SCHED;
	s_add_i32 s34, s56, s39
	v_lshl_add_u64 v[210:211], v[210:211], 0, s[12:13]
	s_mov_b32 m0, s34
	ds_read_b128 v[164:167], v215 offset:49152
	ds_read_b128 v[168:171], v215 offset:50176
	ds_read_b128 v[172:175], v215 offset:51200
	ds_read_b128 v[176:179], v215 offset:52224
	ds_read_b128 v[180:183], v215 offset:53248
	ds_read_b128 v[202:205], v215 offset:54272
	ds_read_b128 v[206:209], v215 offset:55296
	ds_read_b128 v[218:221], v215 offset:56320
	global_load_lds_dwordx4 v[210:211], off
	s_add_i32 m0, s34, 0x2000
	s_add_u32 s30, s30, 0x40080
	v_lshl_add_u64 v[210:211], v[222:223], 0, s[12:13]
	s_addc_u32 s31, s31, 0
	s_add_i32 s34, s57, s39
	global_load_lds_dwordx4 v[210:211], off
	v_lshl_add_u64 v[210:211], s[30:31], 0, v[186:187]
	s_mov_b32 m0, s34
	s_nop 0
	global_load_lds_dwordx4 v[210:211], off
	v_lshl_add_u64 v[210:211], s[30:31], 0, v[190:191]
	s_add_i32 m0, s34, 0x2000
	s_nop 0
	global_load_lds_dwordx4 v[210:211], off
	v_lshl_add_u64 v[210:211], v[224:225], 0, s[12:13]
	s_mov_b32 m0, s46
	s_nop 0
	global_load_lds_dwordx4 v[210:211], off
	v_lshl_add_u64 v[210:211], v[226:227], 0, s[12:13]
	s_mov_b32 m0, s47
	s_nop 0
	global_load_lds_dwordx4 v[210:211], off
	s_add_u32 s27, s27, 0x100
	s_addc_u32 s54, s54, 0
	s_add_u32 s28, s28, 0x100
	s_addc_u32 s29, s29, 0
	s_cmp_eq_u32 s48, s55
	s_cselect_b64 s[30:31], -1, 0
	s_waitcnt vmcnt(8)
	s_waitcnt lgkmcnt(0)
	s_barrier
	s_setprio 1
	v_mfma_f32_16x16x32_bf16 v[60:63], v[132:135], v[164:167], v[60:63]
	v_mfma_f32_16x16x32_bf16 v[56:59], v[140:143], v[164:167], v[56:59]
	v_mfma_f32_16x16x32_bf16 v[44:47], v[132:135], v[172:175], v[44:47]
	v_mfma_f32_16x16x32_bf16 v[40:43], v[140:143], v[172:175], v[40:43]
	v_mfma_f32_16x16x32_bf16 v[28:31], v[132:135], v[180:183], v[28:31]
	v_mfma_f32_16x16x32_bf16 v[24:27], v[140:143], v[180:183], v[24:27]
	v_mfma_f32_16x16x32_bf16 v[12:15], v[132:135], v[206:209], v[12:15]
	v_mfma_f32_16x16x32_bf16 v[8:11], v[140:143], v[206:209], v[8:11]
	v_mfma_f32_16x16x32_bf16 v[60:63], v[136:139], v[168:171], v[60:63]
	v_mfma_f32_16x16x32_bf16 v[56:59], v[144:147], v[168:171], v[56:59]
	v_mfma_f32_16x16x32_bf16 v[44:47], v[136:139], v[176:179], v[44:47]
	v_mfma_f32_16x16x32_bf16 v[40:43], v[144:147], v[176:179], v[40:43]
	v_mfma_f32_16x16x32_bf16 v[28:31], v[136:139], v[202:205], v[28:31]
	v_mfma_f32_16x16x32_bf16 v[24:27], v[144:147], v[202:205], v[24:27]
	v_mfma_f32_16x16x32_bf16 v[12:15], v[136:139], v[218:221], v[12:15]
	v_mfma_f32_16x16x32_bf16 v[8:11], v[144:147], v[218:221], v[8:11]
	v_mfma_f32_16x16x32_bf16 v[52:55], v[148:151], v[164:167], v[52:55]
	v_mfma_f32_16x16x32_bf16 v[48:51], v[156:159], v[164:167], v[48:51]
	v_mfma_f32_16x16x32_bf16 v[36:39], v[148:151], v[172:175], v[36:39]
	v_mfma_f32_16x16x32_bf16 v[32:35], v[156:159], v[172:175], v[32:35]
	v_mfma_f32_16x16x32_bf16 v[20:23], v[148:151], v[180:183], v[20:23]
	v_mfma_f32_16x16x32_bf16 v[16:19], v[156:159], v[180:183], v[16:19]
	v_mfma_f32_16x16x32_bf16 v[4:7], v[148:151], v[206:209], v[4:7]
	v_mfma_f32_16x16x32_bf16 v[0:3], v[156:159], v[206:209], v[0:3]
	v_mfma_f32_16x16x32_bf16 v[52:55], v[152:155], v[168:171], v[52:55]
	v_mfma_f32_16x16x32_bf16 v[48:51], v[160:163], v[168:171], v[48:51]
	v_mfma_f32_16x16x32_bf16 v[36:39], v[152:155], v[176:179], v[36:39]
	v_mfma_f32_16x16x32_bf16 v[32:35], v[160:163], v[176:179], v[32:35]
	v_mfma_f32_16x16x32_bf16 v[20:23], v[152:155], v[202:205], v[20:23]
	v_mfma_f32_16x16x32_bf16 v[16:19], v[160:163], v[202:205], v[16:19]
	v_mfma_f32_16x16x32_bf16 v[4:7], v[152:155], v[218:221], v[4:7]
	v_mfma_f32_16x16x32_bf16 v[0:3], v[160:163], v[218:221], v[0:3]
	s_setprio 0
	s_barrier
	s_cmp_ge_i32 s55, s45
	s_cbranch_scc1 .LBB0_2039
	s_cmp_lg_u32 s48, s55
	s_cbranch_scc1 .LBB0_2036
	s_branch .Lrs_8

; #define LAS __attribute__((address_space(3)))
; template <class Epi>
; __device__ __forceinline__ void gemm_phase(LAS unsigned char* lds, const int tid, const Gemm g, const StaticOrder& S, const Epi& E) {
;     ...
;             if constexpr (Epi::SS_LDS) { if (last) {
;                 const char* sp = (const char*)E.ss + (size_t)cur.pm * (256 * 64) + (size_t)tid * 16;
;                 __builtin_amdgcn_global_load_lds((const unsigned*)sp, (LAS unsigned*)(lds + RS_OFF + ldsw), 16, 0, 0);
;                 __builtin_amdgcn_global_load_lds((const unsigned*)(sp + 8192), (LAS unsigned*)(lds + RS_OFF + 8192 + ldsw), 16, 0, 0); } }
.Lrs_8:
	s_add_i32 m0, s40, 0x20800
	s_nop 0
	global_load_lds_dwordx4 v[128:129], off
	s_add_i32 m0, s40, 0x22800
	s_nop 0
	global_load_lds_dwordx4 v[130:131], off
	s_branch .LBB0_2036
